# NT1: nt hint on the 80 GEMM1 epilogue stores (q/k/v/gates/Z), otherwise M1+Z1+O1+WS1
# speedup vs baseline: 1.0086x; 1.0028x over previous
; __device__ __forceinline__ float silu_f(float z) { return z * __builtin_amdgcn_rcpf(1.0f + __builtin_amdgcn_exp2f(-LOG2E * z)); }
;     __device__ __forceinline__ void operator()(const f32x4 (&acc)[2][2][4][2], const pg8::Unit& u, int ui, LAS unsigned char* lds, int wr, int wc, int fr_, int fq_) const {
;     ...
; #pragma unroll
;             for (int ai = 0; ai < 2; ++ai)
; #pragma unroll
;                 for (int m = 0; m < 4; ++m) {
;                     const int row = row0 + ai * 128 + m * 16;
;                     const float rs = rsv[ai * 4 + m];
;                     float v[2][8];
; #pragma unroll
;                     for (int bj = 0; bj < 2; ++bj)
; #pragma unroll
;                         for (int e = 0; e < 8; ++e) v[bj][e] = acc[ai][bj][m][e >> 2][e & 3] * rs;
;                     if (pn == 2) {
;                         f16* p = V + (size_t)row * 128 + (wc - 2) * 64 + 8 * fq; *(u32x4*)p = pack8(v[0]); *(u32x4*)(p + 32) = pack8(v[1]);
;                     } else if (pn <= 4) {
; #pragma unroll
;                         for (int bj = 0; bj < 2; ++bj)
; #pragma unroll
;                             for (int e = 0; e < 8; ++e) v[bj][e] = silu_f(v[bj][e]);
;                         f16* p = GA + (size_t)row * 512 + (pn - 3) * 256 + wc * 64 + 8 * fq;
;                         *(u32x4*)p = pack8(v[0]); *(u32x4*)(p + 32) = pack8(v[1]);
;                     } else if (pn <= 6) {
; #pragma unroll
;                         for (int bj = 0; bj < 2; ++bj)
; #pragma unroll
;                             for (int e = 0; e < 8; ++e) v[bj][e] = silu_f(v[bj][e]);
;                         const int gq = 2 * (pn - 5) + (wc >> 1), cg8 = 8 * (wc & 1) + fq;
;                         f16* p = GF + ((size_t)(((row >> 12) * 4 + gq) * 16 + cg8) * 4096 + (row & 4095)) * 8;
;                         *(u32x4*)p = pack8(v[0]); *(u32x4*)(p + (size_t)4 * 4096 * 8) = pack8(v[1]);
;                     } else {
;                         const int cg8 = 8 * (wc & 1) + fq;
;                         f16* p = Z + (((size_t)(((row >> 12) * 4 + (pn - 7)) * 16 + cg8) * 4096 + (row & 4095)) * 2 + (wc >> 1)) * 8;
;                         *(u32x4*)p = pack8(v[0]); *(u32x4*)(p + (size_t)4 * 4096 * 16) = pack8(v[1]);
.LBB0_217:
	s_cmp_gt_u32 s13, 4
	s_cselect_b64 s[82:83], -1, 0
	v_sub_co_u32_e64 v150, s[72:73], s13, 7
	s_lshl_b32 s67, s13, 1
	v_mov_b32_e32 v134, v127
	v_mov_b32_e32 v135, v128
	s_xor_b64 s[72:73], s[72:73], -1
	s_add_i32 s67, s67, s65
	s_lshl_b32 s71, s13, 9
	v_pk_mul_f32 v[140:141], v[134:135], v[178:179] op_sel_hi:[1,0]
	v_pk_mov_b32 v[134:135], v[128:129], v[122:123] op_sel:[1,0]
	s_add_u32 vcc_lo, s46, s71
	v_lshlrev_b32_e32 v130, 3, v148
	v_pk_mul_f32 v[144:145], v[134:135], v[178:179] op_sel_hi:[1,0]
	v_mov_b32_e32 v134, v123
	v_mov_b32_e32 v135, v124
	v_pk_mov_b32 v[136:137], v[96:97], v[90:91] op_sel:[1,0]
	s_addc_u32 vcc_hi, s14, 0
	v_ashrrev_i32_e32 v131, 31, v130
	v_pk_mul_f32 v[142:143], v[134:135], v[178:179] op_sel_hi:[1,0]
	v_mov_b32_e32 v134, v95
	v_mov_b32_e32 v135, v96
	v_pk_mul_f32 v[138:139], v[136:137], v[178:179] op_sel_hi:[1,0]
	v_mov_b32_e32 v136, v91
	v_mov_b32_e32 v137, v92
	v_add_u32_e32 v149, s36, v148
	v_lshl_add_u64 v[132:133], v[130:131], 1, vcc
	v_mul_f32_e32 v151, v126, v178
	v_mul_f32_e32 v152, v125, v178
	v_mul_f32_e32 v147, v94, v178
	v_pk_mul_f32 v[134:135], v[134:135], v[178:179] op_sel_hi:[1,0]
	v_pk_mul_f32 v[136:137], v[136:137], v[178:179] op_sel_hi:[1,0]
	v_mul_f32_e32 v146, v93, v178
	s_and_b64 vcc, exec, s[78:79]
	s_cbranch_vccz .LBB0_227
	s_and_b64 vcc, exec, s[82:83]
	s_cbranch_vccz .LBB0_224
	v_ashrrev_i32_e32 v153, 10, v164
	s_and_b64 vcc, exec, s[72:73]
	v_and_b32_e32 v153, 0xffffffc, v153
	s_cbranch_vccz .LBB0_221
	v_add_u32_e32 v165, v153, v150
	v_lshl_add_u32 v180, v165, 4, v149
	v_ashrrev_i32_e32 v181, 31, v180
	v_lshlrev_b64 v[180:181], 13, v[180:181]
	s_movk_i32 s10, 0xfff
	v_and_or_b32 v165, v164, s10, v180
	v_lshl_or_b32 v180, s64, 12, v165
	s_nop 0
	v_lshl_add_u64 v[184:185], v[180:181], 4, s[16:17]
	v_cvt_pk_f16_f32 v183, v143, v152
	v_cvt_pk_f16_f32 v182, v145, v142
	v_cvt_pk_f16_f32 v181, v141, v144
	v_cvt_pk_f16_f32 v180, v151, v140
	global_store_dwordx4 v[184:185], v[180:183], off nt
	v_add_co_u32_e32 v184, vcc, 0x80000, v184
	s_nop 0
	v_cvt_pk_f16_f32 v183, v137, v146
	v_cvt_pk_f16_f32 v182, v139, v136
	v_cvt_pk_f16_f32 v181, v135, v138
	v_cvt_pk_f16_f32 v180, v147, v134
	v_addc_co_u32_e32 v185, vcc, 0, v185, vcc
	global_store_dwordx4 v[184:185], v[180:183], off nt
	s_mov_b64 s[10:11], 0
.LBB0_221:
	s_andn2_b64 vcc, exec, s[10:11]
	s_cbranch_vccnz .LBB0_223
	v_mul_f32_e32 v173, 0xbfb8aa3b, v140
	v_exp_f32_e32 v173, v173
	v_mul_f32_e32 v175, 0xbfb8aa3b, v141
	v_exp_f32_e32 v175, v175
	v_mul_f32_e32 v177, 0xbfb8aa3b, v144
	v_exp_f32_e32 v177, v177
	v_add_f32_e32 v173, 1.0, v173
	v_rcp_f32_e32 v180, v173
	v_add_f32_e32 v173, 1.0, v175
	v_mul_f32_e32 v175, 0xbfb8aa3b, v145
	v_rcp_f32_e32 v181, v173
	v_add_f32_e32 v173, 1.0, v177
	v_exp_f32_e32 v175, v175
	v_mul_f32_e32 v177, 0xbfb8aa3b, v142
	v_exp_f32_e32 v177, v177
	v_rcp_f32_e32 v182, v173
	v_add_f32_e32 v173, 1.0, v175
	v_mul_f32_e32 v175, 0xbfb8aa3b, v143
	v_rcp_f32_e32 v183, v173
	v_add_f32_e32 v173, 1.0, v177
	v_exp_f32_e32 v175, v175
	v_mul_f32_e32 v177, 0xbfb8aa3b, v152
	v_exp_f32_e32 v177, v177
	v_rcp_f32_e32 v184, v173
	v_add_f32_e32 v173, 1.0, v175
	v_rcp_f32_e32 v185, v173
	v_add_f32_e32 v173, 1.0, v177
	v_mul_f32_e32 v177, 0xbfb8aa3b, v134
	v_exp_f32_e32 v177, v177
	v_mul_f32_e32 v179, 0xbfb8aa3b, v135
	v_exp_f32_e32 v179, v179
	v_mul_f32_e32 v186, 0xbfb8aa3b, v138
	v_exp_f32_e32 v188, v186
	v_add_f32_e32 v177, 1.0, v177
	v_rcp_f32_e32 v186, v177
	v_add_f32_e32 v177, 1.0, v179
	v_mul_f32_e32 v179, 0xbfb8aa3b, v139
	v_rcp_f32_e32 v187, v177
	v_add_f32_e32 v177, 1.0, v188
	v_exp_f32_e32 v179, v179
	v_mul_f32_e32 v188, 0xbfb8aa3b, v136
	v_mul_f32_e32 v165, 0xbfb8aa3b, v151
	v_exp_f32_e32 v190, v188
	v_exp_f32_e32 v165, v165
	v_rcp_f32_e32 v188, v177
	v_add_f32_e32 v177, 1.0, v179
	v_mul_f32_e32 v179, 0xbfb8aa3b, v137
	v_rcp_f32_e32 v189, v177
	v_add_f32_e32 v177, 1.0, v190
	v_exp_f32_e32 v179, v179
	v_mul_f32_e32 v190, 0xbfb8aa3b, v146
	v_add_f32_e32 v165, 1.0, v165
	v_exp_f32_e32 v192, v190
	v_rcp_f32_e32 v165, v165
	v_mul_f32_e32 v175, 0xbfb8aa3b, v147
	v_exp_f32_e32 v175, v175
	v_rcp_f32_e32 v190, v177
	v_add_f32_e32 v177, 1.0, v179
	v_add_u32_e32 v153, s67, v153
	v_rcp_f32_e32 v191, v177
	v_add_f32_e32 v177, 1.0, v192
	v_lshl_add_u32 v192, v153, 4, v149
	v_lshlrev_b32_e32 v153, 4, v164
	v_pk_mul_f32 v[180:181], v[140:141], v[180:181]
	v_rcp_f32_e32 v173, v173
	v_and_b32_e32 v194, 0xfff0, v153
	v_fma_mixlo_f16 v153, v151, v165, 0
	v_cvt_pk_f16_f32 v165, v180, v181
	v_pk_mul_f32 v[182:183], v[144:145], v[182:183]
	v_add_f32_e32 v175, 1.0, v175
	v_ashrrev_i32_e32 v193, 31, v192
	v_readlane_b32 s10, v254, 6
	v_pack_b32_f16 v180, v153, v165
	v_cvt_pk_f16_f32 v153, v182, v183
	v_pk_mul_f32 v[182:183], v[142:143], v[184:185]
	v_rcp_f32_e32 v175, v175
	v_lshlrev_b64 v[192:193], 16, v[192:193]
	v_readlane_b32 s11, v254, 7
	v_alignbit_b32 v181, v153, v165, 16
	v_cvt_pk_f16_f32 v165, v182, v183
	v_lshl_add_u64 v[192:193], s[10:11], 0, v[192:193]
	v_lshrrev_b32_e32 v183, 16, v165
	v_lshl_add_u64 v[192:193], v[192:193], 0, v[194:195]
	v_alignbit_b32 v182, v165, v153, 16
	v_fma_mixhi_f16 v183, v152, v173, 0
	global_store_dwordx4 v[192:193], v[180:183], off nt
	v_rcp_f32_e32 v177, v177
	v_fma_mixlo_f16 v153, v147, v175, 0
	v_pk_mul_f32 v[180:181], v[134:135], v[186:187]
	v_pk_mul_f32 v[182:183], v[138:139], v[188:189]
	v_cvt_pk_f16_f32 v165, v180, v181
	v_pack_b32_f16 v180, v153, v165
	v_cvt_pk_f16_f32 v153, v182, v183
	v_pk_mul_f32 v[182:183], v[136:137], v[190:191]
	v_alignbit_b32 v181, v153, v165, 16
	v_cvt_pk_f16_f32 v165, v182, v183
	v_lshrrev_b32_e32 v183, 16, v165
	v_add_co_u32_e32 v184, vcc, 0x40000, v192
	v_alignbit_b32 v182, v165, v153, 16
	v_fma_mixhi_f16 v183, v146, v177, 0
	v_addc_co_u32_e32 v185, vcc, 0, v193, vcc
	global_store_dwordx4 v[184:185], v[180:183], off nt

; __device__ __forceinline__ float silu_f(float z) { return z * __builtin_amdgcn_rcpf(1.0f + __builtin_amdgcn_exp2f(-LOG2E * z)); }
;     __device__ __forceinline__ void operator()(const f32x4 (&acc)[2][2][4][2], const pg8::Unit& u, int ui, LAS unsigned char* lds, int wr, int wc, int fr_, int fq_) const {
;     ...
;                     } else if (pn <= 4) {
; #pragma unroll
;                         for (int bj = 0; bj < 2; ++bj)
; #pragma unroll
;                             for (int e = 0; e < 8; ++e) v[bj][e] = silu_f(v[bj][e]);
;                         f16* p = GA + (size_t)row * 512 + (pn - 3) * 256 + wc * 64 + 8 * fq;
;                         *(u32x4*)p = pack8(v[0]); *(u32x4*)(p + 32) = pack8(v[1]);
.LBB0_224:
	s_andn2_b64 vcc, exec, s[10:11]
	s_cbranch_vccnz .LBB0_226
	v_mul_f32_e32 v165, 0xbfb8aa3b, v140
	v_exp_f32_e32 v165, v165
	v_mul_f32_e32 v173, 0xbfb8aa3b, v141
	v_exp_f32_e32 v173, v173
	v_mul_f32_e32 v175, 0xbfb8aa3b, v144
	v_exp_f32_e32 v175, v175
	v_add_f32_e32 v165, 1.0, v165
	v_rcp_f32_e32 v180, v165
	v_add_f32_e32 v165, 1.0, v173
	v_mul_f32_e32 v173, 0xbfb8aa3b, v145
	v_rcp_f32_e32 v181, v165
	v_add_f32_e32 v165, 1.0, v175
	v_exp_f32_e32 v173, v173
	v_mul_f32_e32 v175, 0xbfb8aa3b, v142
	v_exp_f32_e32 v175, v175
	v_rcp_f32_e32 v182, v165
	v_add_f32_e32 v165, 1.0, v173
	v_mul_f32_e32 v173, 0xbfb8aa3b, v143
	v_rcp_f32_e32 v183, v165
	v_add_f32_e32 v165, 1.0, v175
	v_exp_f32_e32 v173, v173
	v_mul_f32_e32 v175, 0xbfb8aa3b, v152
	v_exp_f32_e32 v175, v175
	v_rcp_f32_e32 v184, v165
	v_add_f32_e32 v165, 1.0, v173
	v_mul_f32_e32 v173, 0xbfb8aa3b, v147
	v_rcp_f32_e32 v185, v165
	v_add_f32_e32 v165, 1.0, v175
	v_exp_f32_e32 v173, v173
	v_mul_f32_e32 v175, 0xbfb8aa3b, v134
	v_exp_f32_e32 v175, v175
	v_rcp_f32_e32 v177, v165
	v_add_f32_e32 v165, 1.0, v173
	v_rcp_f32_e32 v173, v165
	v_add_f32_e32 v165, 1.0, v175
	v_mul_f32_e32 v175, 0xbfb8aa3b, v135
	v_exp_f32_e32 v175, v175
	v_mul_f32_e32 v179, 0xbfb8aa3b, v138
	v_exp_f32_e32 v179, v179
	v_rcp_f32_e32 v186, v165
	v_add_f32_e32 v165, 1.0, v175
	v_mul_f32_e32 v175, 0xbfb8aa3b, v139
	v_rcp_f32_e32 v187, v165
	v_add_f32_e32 v165, 1.0, v179
	v_exp_f32_e32 v175, v175
	v_mul_f32_e32 v179, 0xbfb8aa3b, v136
	v_exp_f32_e32 v179, v179
	v_mul_f32_e32 v153, 0xbfb8aa3b, v151
	v_exp_f32_e32 v153, v153
	v_rcp_f32_e32 v188, v165
	v_add_f32_e32 v165, 1.0, v175
	v_mul_f32_e32 v175, 0xbfb8aa3b, v137
	v_rcp_f32_e32 v189, v165
	v_add_f32_e32 v165, 1.0, v179
	v_exp_f32_e32 v175, v175
	v_mul_f32_e32 v179, 0xbfb8aa3b, v146
	v_exp_f32_e32 v179, v179
	v_add_f32_e32 v153, 1.0, v153
	v_rcp_f32_e32 v153, v153
	v_rcp_f32_e32 v190, v165
	v_add_f32_e32 v165, 1.0, v175
	v_rcp_f32_e32 v191, v165
	v_add_f32_e32 v165, 1.0, v179
	v_rcp_f32_e32 v175, v165
	v_ashrrev_i32_e32 v165, 31, v164
	v_pk_mul_f32 v[180:181], v[140:141], v[180:181]
	v_lshlrev_b64 v[192:193], 10, v[164:165]
	v_fma_mixlo_f16 v153, v151, v153, 0
	v_cvt_pk_f16_f32 v165, v180, v181
	v_pk_mul_f32 v[182:183], v[144:145], v[182:183]
	v_pack_b32_f16 v180, v153, v165
	v_cvt_pk_f16_f32 v153, v182, v183
	v_pk_mul_f32 v[182:183], v[142:143], v[184:185]
	v_alignbit_b32 v181, v153, v165, 16
	v_cvt_pk_f16_f32 v165, v182, v183
	v_lshrrev_b32_e32 v183, 16, v165
	v_lshl_add_u64 v[192:193], v[132:133], 0, v[192:193]
	v_alignbit_b32 v182, v165, v153, 16
	v_fma_mixhi_f16 v183, v152, v177, 0
	global_store_dwordx4 v[192:193], v[180:183], off offset:-1536 nt
	v_fma_mixlo_f16 v153, v147, v173, 0
	s_nop 0
	v_pk_mul_f32 v[180:181], v[134:135], v[186:187]
	v_pk_mul_f32 v[182:183], v[138:139], v[188:189]
	v_cvt_pk_f16_f32 v165, v180, v181
	v_pack_b32_f16 v180, v153, v165
	v_cvt_pk_f16_f32 v153, v182, v183
	v_pk_mul_f32 v[182:183], v[136:137], v[190:191]
	v_alignbit_b32 v181, v153, v165, 16
	v_cvt_pk_f16_f32 v165, v182, v183
	v_lshrrev_b32_e32 v183, 16, v165
	v_alignbit_b32 v182, v165, v153, 16
	v_fma_mixhi_f16 v183, v146, v175, 0
	global_store_dwordx4 v[192:193], v[180:183], off offset:-1472 nt

; __device__ __forceinline__ float silu_f(float z) { return z * __builtin_amdgcn_rcpf(1.0f + __builtin_amdgcn_exp2f(-LOG2E * z)); }
;     __device__ __forceinline__ void operator()(const f32x4 (&acc)[2][2][4][2], const pg8::Unit& u, int ui, LAS unsigned char* lds, int wr, int wc, int fr_, int fq_) const {
;     ...
;                 for (int m = 0; m < 4; ++m) {
;                     const int row = row0 + ai * 128 + m * 16;
;                     const float rs = rsv[ai * 4 + m];
;                     float v[2][8];
; #pragma unroll
;                     for (int bj = 0; bj < 2; ++bj)
; #pragma unroll
;                         for (int e = 0; e < 8; ++e) v[bj][e] = acc[ai][bj][m][e >> 2][e & 3] * rs;
;                     if (pn == 2) {
;                         f16* p = V + (size_t)row * 128 + (wc - 2) * 64 + 8 * fq; *(u32x4*)p = pack8(v[0]); *(u32x4*)(p + 32) = pack8(v[1]);
;                     } else if (pn <= 4) {
; #pragma unroll
;                         for (int bj = 0; bj < 2; ++bj)
; #pragma unroll
;                             for (int e = 0; e < 8; ++e) v[bj][e] = silu_f(v[bj][e]);
;                         f16* p = GA + (size_t)row * 512 + (pn - 3) * 256 + wc * 64 + 8 * fq;
;                         *(u32x4*)p = pack8(v[0]); *(u32x4*)(p + 32) = pack8(v[1]);
;                     } else if (pn <= 6) {
; #pragma unroll
;                         for (int bj = 0; bj < 2; ++bj)
; #pragma unroll
;                             for (int e = 0; e < 8; ++e) v[bj][e] = silu_f(v[bj][e]);
;                         const int gq = 2 * (pn - 5) + (wc >> 1), cg8 = 8 * (wc & 1) + fq;
;                         f16* p = GF + ((size_t)(((row >> 12) * 4 + gq) * 16 + cg8) * 4096 + (row & 4095)) * 8;
;                         *(u32x4*)p = pack8(v[0]); *(u32x4*)(p + (size_t)4 * 4096 * 8) = pack8(v[1]);
;                     } else {
;                         const int cg8 = 8 * (wc & 1) + fq;
;                         f16* p = Z + (((size_t)(((row >> 12) * 4 + (pn - 7)) * 16 + cg8) * 4096 + (row & 4095)) * 2 + (wc >> 1)) * 8;
;                         *(u32x4*)p = pack8(v[0]); *(u32x4*)(p + (size_t)4 * 4096 * 16) = pack8(v[1]);
.LBB0_227:
	s_andn2_b64 vcc, exec, s[10:11]
	s_cbranch_vccnz .LBB0_229
	v_ashrrev_i32_e32 v165, 31, v164
	v_lshlrev_b64 v[180:181], 8, v[164:165]
	v_cvt_f16_f32_e32 v151, v151
	v_lshl_add_u64 v[180:181], s[80:81], 0, v[180:181]
	v_cvt_pk_f16_f32 v144, v144, v145
	v_cvt_f16_f32_e32 v145, v152
	v_cvt_f16_f32_e32 v147, v147
	v_cvt_pk_f16_f32 v138, v138, v139
	v_cvt_f16_f32_e32 v139, v146
	v_lshl_add_u64 v[180:181], v[130:131], 1, v[180:181]
	s_mov_b64 s[10:11], 0x9bfff00
	v_lshl_add_u64 v[182:183], v[180:181], 0, s[10:11]
	v_cvt_pk_f16_f32 v141, v140, v141
	v_cvt_pk_f16_f32 v143, v142, v143
	s_mov_b32 s10, 0x9bff000
	v_pack_b32_f16 v140, v151, v141
	v_alignbit_b32 v141, v144, v141, 16
	v_alignbit_b32 v142, v143, v144, 16
	v_add_co_u32_e32 v144, vcc, s10, v180
	v_cvt_pk_f16_f32 v135, v134, v135
	v_cvt_pk_f16_f32 v137, v136, v137
	v_alignbit_b32 v143, v145, v143, 16
	v_addc_co_u32_e32 v145, vcc, 0, v181, vcc
	v_pack_b32_f16 v134, v147, v135
	v_alignbit_b32 v135, v138, v135, 16
	v_alignbit_b32 v136, v137, v138, 16
	v_alignbit_b32 v137, v139, v137, 16
	global_store_dwordx4 v[144:145], v[140:143], off offset:3840 nt
	global_store_dwordx4 v[182:183], v[134:137], off offset:64 nt
.LBB0_229:
	s_nop 1
	v_mov_b32_e32 v134, v119
	v_mov_b32_e32 v135, v120
	v_pk_mul_f32 v[140:141], v[134:135], v[176:177] op_sel_hi:[1,0]
	v_pk_mov_b32 v[134:135], v[120:121], v[114:115] op_sel:[1,0]
	v_pk_mov_b32 v[136:137], v[88:89], v[82:83] op_sel:[1,0]
	v_pk_mul_f32 v[144:145], v[134:135], v[176:177] op_sel_hi:[1,0]
	v_mov_b32_e32 v134, v115
	v_mov_b32_e32 v135, v116
	v_pk_mul_f32 v[142:143], v[134:135], v[176:177] op_sel_hi:[1,0]
	v_mov_b32_e32 v134, v87
	v_mov_b32_e32 v135, v88
	v_pk_mul_f32 v[138:139], v[136:137], v[176:177] op_sel_hi:[1,0]
	v_mov_b32_e32 v136, v83
	v_mov_b32_e32 v137, v84
	v_cndmask_b32_e64 v147, 0, 1, s[78:79]
	v_mul_f32_e32 v153, v118, v176
	v_mul_f32_e32 v165, v117, v176
	v_mul_f32_e32 v152, v86, v176
	v_pk_mul_f32 v[134:135], v[134:135], v[176:177] op_sel_hi:[1,0]
	v_pk_mul_f32 v[136:137], v[136:137], v[176:177] op_sel_hi:[1,0]
	v_mul_f32_e32 v151, v85, v176
	v_add_u32_e32 v146, 16, v164
	v_cmp_ne_u32_e64 s[10:11], 1, v147
	s_andn2_b64 vcc, exec, s[78:79]
	s_mov_b64 s[78:79], -1
	s_cbranch_vccnz .LBB0_239
	s_andn2_b64 vcc, exec, s[82:83]
	s_cbranch_vccnz .LBB0_236
	v_ashrrev_i32_e32 v147, 10, v146
	s_andn2_b64 vcc, exec, s[72:73]
	v_and_b32_e32 v147, 0xffffffc, v147
	s_cbranch_vccnz .LBB0_233
	v_add_u32_e32 v173, v147, v150
	v_lshl_add_u32 v180, v173, 4, v149
	v_ashrrev_i32_e32 v181, 31, v180
	v_lshlrev_b64 v[180:181], 13, v[180:181]
	s_movk_i32 s71, 0xfff
	v_and_or_b32 v173, v146, s71, v180
	v_lshl_or_b32 v180, s64, 12, v173
	s_nop 0
	v_lshl_add_u64 v[184:185], v[180:181], 4, s[16:17]
	v_cvt_pk_f16_f32 v183, v143, v165
	v_cvt_pk_f16_f32 v182, v145, v142
	v_cvt_pk_f16_f32 v181, v141, v144
	v_cvt_pk_f16_f32 v180, v153, v140
	global_store_dwordx4 v[184:185], v[180:183], off nt
	v_add_co_u32_e32 v184, vcc, 0x80000, v184
	s_nop 0
	v_cvt_pk_f16_f32 v183, v137, v151
	v_cvt_pk_f16_f32 v182, v139, v136
	v_cvt_pk_f16_f32 v181, v135, v138
	v_cvt_pk_f16_f32 v180, v152, v134
	v_addc_co_u32_e32 v185, vcc, 0, v185, vcc
	s_mov_b64 s[78:79], 0
	global_store_dwordx4 v[184:185], v[180:183], off nt
.LBB0_233:
	s_andn2_b64 vcc, exec, s[78:79]
	s_cbranch_vccnz .LBB0_235
	v_mul_f32_e32 v175, 0xbfb8aa3b, v140
	v_exp_f32_e32 v175, v175
	v_mul_f32_e32 v177, 0xbfb8aa3b, v141
	v_exp_f32_e32 v177, v177
	v_mul_f32_e32 v179, 0xbfb8aa3b, v144
	v_exp_f32_e32 v179, v179
	v_add_f32_e32 v175, 1.0, v175
	v_rcp_f32_e32 v180, v175
	v_add_f32_e32 v175, 1.0, v177
	v_mul_f32_e32 v177, 0xbfb8aa3b, v145
	v_rcp_f32_e32 v181, v175
	v_add_f32_e32 v175, 1.0, v179
	v_exp_f32_e32 v177, v177
	v_mul_f32_e32 v179, 0xbfb8aa3b, v142
	v_exp_f32_e32 v179, v179
	v_rcp_f32_e32 v182, v175
	v_add_f32_e32 v175, 1.0, v177
	v_mul_f32_e32 v177, 0xbfb8aa3b, v143
	v_rcp_f32_e32 v183, v175
	v_add_f32_e32 v175, 1.0, v179
	v_exp_f32_e32 v177, v177
	v_mul_f32_e32 v179, 0xbfb8aa3b, v165
	v_exp_f32_e32 v179, v179
	v_rcp_f32_e32 v184, v175
	v_add_f32_e32 v175, 1.0, v177
	v_rcp_f32_e32 v185, v175
	v_add_f32_e32 v175, 1.0, v179
	v_mul_f32_e32 v179, 0xbfb8aa3b, v134
	v_exp_f32_e32 v179, v179
	v_mul_f32_e32 v186, 0xbfb8aa3b, v135
	v_exp_f32_e32 v187, v186
	v_mul_f32_e32 v186, 0xbfb8aa3b, v138
	v_exp_f32_e32 v188, v186
	v_add_f32_e32 v179, 1.0, v179
	v_rcp_f32_e32 v186, v179
	v_add_f32_e32 v179, 1.0, v187
	v_rcp_f32_e32 v187, v179
	v_add_f32_e32 v179, 1.0, v188
	v_mul_f32_e32 v188, 0xbfb8aa3b, v139
	v_exp_f32_e32 v189, v188
	v_mul_f32_e32 v188, 0xbfb8aa3b, v136
	v_exp_f32_e32 v190, v188
	v_mul_f32_e32 v173, 0xbfb8aa3b, v153
	v_exp_f32_e32 v173, v173
	v_rcp_f32_e32 v188, v179
	v_add_f32_e32 v179, 1.0, v189
	v_rcp_f32_e32 v189, v179
	v_add_f32_e32 v179, 1.0, v190
	v_mul_f32_e32 v190, 0xbfb8aa3b, v137
	v_exp_f32_e32 v191, v190
	v_mul_f32_e32 v190, 0xbfb8aa3b, v151
	v_add_f32_e32 v173, 1.0, v173
	v_exp_f32_e32 v192, v190
	v_rcp_f32_e32 v173, v173
	v_mul_f32_e32 v177, 0xbfb8aa3b, v152
	v_exp_f32_e32 v177, v177
	v_rcp_f32_e32 v190, v179
	v_add_f32_e32 v179, 1.0, v191
	v_add_u32_e32 v147, s67, v147
	v_rcp_f32_e32 v191, v179
	v_add_f32_e32 v179, 1.0, v192
	v_lshl_add_u32 v192, v147, 4, v149
	v_lshlrev_b32_e32 v147, 4, v146
	v_pk_mul_f32 v[180:181], v[140:141], v[180:181]
	v_rcp_f32_e32 v175, v175
	v_and_b32_e32 v194, 0xfff0, v147
	v_fma_mixlo_f16 v147, v153, v173, 0
	v_cvt_pk_f16_f32 v173, v180, v181
	v_pk_mul_f32 v[182:183], v[144:145], v[182:183]
	v_add_f32_e32 v177, 1.0, v177
	v_ashrrev_i32_e32 v193, 31, v192
	v_readlane_b32 s74, v254, 6
	v_pack_b32_f16 v180, v147, v173
	v_cvt_pk_f16_f32 v147, v182, v183
	v_pk_mul_f32 v[182:183], v[142:143], v[184:185]
	v_rcp_f32_e32 v177, v177
	v_lshlrev_b64 v[192:193], 16, v[192:193]
	v_readlane_b32 s75, v254, 7
	v_alignbit_b32 v181, v147, v173, 16
	v_cvt_pk_f16_f32 v173, v182, v183
	v_lshl_add_u64 v[192:193], s[74:75], 0, v[192:193]
	v_lshrrev_b32_e32 v183, 16, v173
	v_lshl_add_u64 v[192:193], v[192:193], 0, v[194:195]
	v_alignbit_b32 v182, v173, v147, 16
	v_fma_mixhi_f16 v183, v165, v175, 0
	global_store_dwordx4 v[192:193], v[180:183], off nt
	v_rcp_f32_e32 v179, v179
	v_fma_mixlo_f16 v147, v152, v177, 0
	v_pk_mul_f32 v[180:181], v[134:135], v[186:187]
	v_pk_mul_f32 v[182:183], v[138:139], v[188:189]
	v_cvt_pk_f16_f32 v173, v180, v181
	v_pack_b32_f16 v180, v147, v173
	v_cvt_pk_f16_f32 v147, v182, v183
	v_pk_mul_f32 v[182:183], v[136:137], v[190:191]
	v_alignbit_b32 v181, v147, v173, 16
	v_cvt_pk_f16_f32 v173, v182, v183
	v_lshrrev_b32_e32 v183, 16, v173
	v_add_co_u32_e32 v184, vcc, 0x40000, v192
	v_alignbit_b32 v182, v173, v147, 16
	v_fma_mixhi_f16 v183, v151, v179, 0
	v_addc_co_u32_e32 v185, vcc, 0, v193, vcc
	global_store_dwordx4 v[184:185], v[180:183], off nt

; __device__ __forceinline__ float silu_f(float z) { return z * __builtin_amdgcn_rcpf(1.0f + __builtin_amdgcn_exp2f(-LOG2E * z)); }
;     __device__ __forceinline__ void operator()(const f32x4 (&acc)[2][2][4][2], const pg8::Unit& u, int ui, LAS unsigned char* lds, int wr, int wc, int fr_, int fq_) const {
;     ...
;                     } else if (pn <= 4) {
; #pragma unroll
;                         for (int bj = 0; bj < 2; ++bj)
; #pragma unroll
;                             for (int e = 0; e < 8; ++e) v[bj][e] = silu_f(v[bj][e]);
;                         f16* p = GA + (size_t)row * 512 + (pn - 3) * 256 + wc * 64 + 8 * fq;
;                         *(u32x4*)p = pack8(v[0]); *(u32x4*)(p + 32) = pack8(v[1]);
.LBB0_236:
	s_andn2_b64 vcc, exec, s[78:79]
	s_cbranch_vccnz .LBB0_238
	v_mul_f32_e32 v147, 0xbfb8aa3b, v153
	v_exp_f32_e32 v147, v147
	v_mul_f32_e32 v173, 0xbfb8aa3b, v140
	v_exp_f32_e32 v173, v173
	v_mul_f32_e32 v177, 0xbfb8aa3b, v144
	v_add_f32_e32 v147, 1.0, v147
	v_rcp_f32_e32 v175, v147
	v_mul_f32_e32 v147, 0xbfb8aa3b, v141
	v_exp_f32_e32 v147, v147
	v_exp_f32_e32 v177, v177
	v_add_f32_e32 v173, 1.0, v173
	v_rcp_f32_e32 v180, v173
	v_add_f32_e32 v147, 1.0, v147
	v_mul_f32_e32 v173, 0xbfb8aa3b, v145
	v_rcp_f32_e32 v181, v147
	v_add_f32_e32 v147, 1.0, v177
	v_exp_f32_e32 v173, v173
	v_mul_f32_e32 v177, 0xbfb8aa3b, v142
	v_exp_f32_e32 v177, v177
	v_rcp_f32_e32 v182, v147
	v_add_f32_e32 v147, 1.0, v173
	v_mul_f32_e32 v173, 0xbfb8aa3b, v143
	v_rcp_f32_e32 v183, v147
	v_add_f32_e32 v147, 1.0, v177
	v_exp_f32_e32 v173, v173
	v_mul_f32_e32 v177, 0xbfb8aa3b, v165
	v_exp_f32_e32 v177, v177
	v_rcp_f32_e32 v184, v147
	v_add_f32_e32 v147, 1.0, v173
	v_mul_f32_e32 v173, 0xbfb8aa3b, v152
	v_rcp_f32_e32 v185, v147
	v_add_f32_e32 v147, 1.0, v177
	v_exp_f32_e32 v173, v173
	v_mul_f32_e32 v177, 0xbfb8aa3b, v134
	v_exp_f32_e32 v177, v177
	v_rcp_f32_e32 v179, v147
	v_add_f32_e32 v147, 1.0, v173
	v_rcp_f32_e32 v173, v147
	v_add_f32_e32 v147, 1.0, v177
	v_mul_f32_e32 v177, 0xbfb8aa3b, v135
	v_exp_f32_e32 v177, v177
	v_mul_f32_e32 v186, 0xbfb8aa3b, v138
	v_exp_f32_e32 v188, v186
	v_rcp_f32_e32 v186, v147
	v_add_f32_e32 v147, 1.0, v177
	v_mul_f32_e32 v177, 0xbfb8aa3b, v139
	v_rcp_f32_e32 v187, v147
	v_add_f32_e32 v147, 1.0, v188
	v_exp_f32_e32 v177, v177
	v_mul_f32_e32 v188, 0xbfb8aa3b, v136
	v_exp_f32_e32 v190, v188
	v_rcp_f32_e32 v188, v147
	v_add_f32_e32 v147, 1.0, v177
	v_mul_f32_e32 v177, 0xbfb8aa3b, v137
	v_rcp_f32_e32 v189, v147
	v_add_f32_e32 v147, 1.0, v190
	v_exp_f32_e32 v177, v177
	v_mul_f32_e32 v190, 0xbfb8aa3b, v151
	v_exp_f32_e32 v192, v190
	v_rcp_f32_e32 v190, v147
	v_add_f32_e32 v147, 1.0, v177
	v_rcp_f32_e32 v191, v147
	v_add_f32_e32 v147, 1.0, v192
	v_rcp_f32_e32 v177, v147
	v_ashrrev_i32_e32 v147, 31, v146
	v_pk_mul_f32 v[180:181], v[140:141], v[180:181]
	v_lshlrev_b64 v[192:193], 10, v[146:147]
	v_fma_mixlo_f16 v147, v153, v175, 0
	v_cvt_pk_f16_f32 v175, v180, v181
	v_pk_mul_f32 v[182:183], v[144:145], v[182:183]
	v_pack_b32_f16 v180, v147, v175
	v_cvt_pk_f16_f32 v147, v182, v183
	v_pk_mul_f32 v[182:183], v[142:143], v[184:185]
	v_alignbit_b32 v181, v147, v175, 16
	v_cvt_pk_f16_f32 v175, v182, v183
	v_lshrrev_b32_e32 v183, 16, v175
	v_lshl_add_u64 v[192:193], v[132:133], 0, v[192:193]
	v_alignbit_b32 v182, v175, v147, 16
	v_fma_mixhi_f16 v183, v165, v179, 0
	global_store_dwordx4 v[192:193], v[180:183], off offset:-1536 nt
	v_fma_mixlo_f16 v147, v152, v173, 0
	s_nop 0
	v_pk_mul_f32 v[180:181], v[134:135], v[186:187]
	v_pk_mul_f32 v[182:183], v[138:139], v[188:189]
	v_cvt_pk_f16_f32 v173, v180, v181
	v_pack_b32_f16 v180, v147, v173
	v_cvt_pk_f16_f32 v147, v182, v183
	v_pk_mul_f32 v[182:183], v[136:137], v[190:191]
	v_alignbit_b32 v181, v147, v173, 16
	v_cvt_pk_f16_f32 v173, v182, v183
	v_lshrrev_b32_e32 v183, 16, v173
	v_alignbit_b32 v182, v173, v147, 16
	v_fma_mixhi_f16 v183, v151, v177, 0
	global_store_dwordx4 v[192:193], v[180:183], off offset:-1472 nt

; __device__ __forceinline__ float silu_f(float z) { return z * __builtin_amdgcn_rcpf(1.0f + __builtin_amdgcn_exp2f(-LOG2E * z)); }
;     __device__ __forceinline__ void operator()(const f32x4 (&acc)[2][2][4][2], const pg8::Unit& u, int ui, LAS unsigned char* lds, int wr, int wc, int fr_, int fq_) const {
;     ...
;                     if (pn == 2) {
;                         f16* p = V + (size_t)row * 128 + (wc - 2) * 64 + 8 * fq; *(u32x4*)p = pack8(v[0]); *(u32x4*)(p + 32) = pack8(v[1]);
;                     } else if (pn <= 4) {
; #pragma unroll
;                         for (int bj = 0; bj < 2; ++bj)
; #pragma unroll
;                             for (int e = 0; e < 8; ++e) v[bj][e] = silu_f(v[bj][e]);
;                         f16* p = GA + (size_t)row * 512 + (pn - 3) * 256 + wc * 64 + 8 * fq;
;                         *(u32x4*)p = pack8(v[0]); *(u32x4*)(p + 32) = pack8(v[1]);
;                     } else if (pn <= 6) {
; #pragma unroll
;                         for (int bj = 0; bj < 2; ++bj)
; #pragma unroll
;                             for (int e = 0; e < 8; ++e) v[bj][e] = silu_f(v[bj][e]);
;                         const int gq = 2 * (pn - 5) + (wc >> 1), cg8 = 8 * (wc & 1) + fq;
;                         f16* p = GF + ((size_t)(((row >> 12) * 4 + gq) * 16 + cg8) * 4096 + (row & 4095)) * 8;
;                         *(u32x4*)p = pack8(v[0]); *(u32x4*)(p + (size_t)4 * 4096 * 8) = pack8(v[1]);
;                     } else {
;                         const int cg8 = 8 * (wc & 1) + fq;
;                         f16* p = Z + (((size_t)(((row >> 12) * 4 + (pn - 7)) * 16 + cg8) * 4096 + (row & 4095)) * 2 + (wc >> 1)) * 8;
;                         *(u32x4*)p = pack8(v[0]); *(u32x4*)(p + (size_t)4 * 4096 * 16) = pack8(v[1]);
.LBB0_239:
	s_andn2_b64 vcc, exec, s[78:79]
	s_cbranch_vccnz .LBB0_241
	v_ashrrev_i32_e32 v147, 31, v146
	v_cvt_f16_f32_e32 v153, v153
	v_lshlrev_b64 v[146:147], 8, v[146:147]
	v_lshl_add_u64 v[146:147], s[80:81], 0, v[146:147]
	v_lshl_add_u64 v[146:147], v[130:131], 1, v[146:147]
	s_mov_b64 s[74:75], 0x9bfff00
	v_cvt_pk_f16_f32 v141, v140, v141
	v_cvt_pk_f16_f32 v144, v144, v145
	v_cvt_pk_f16_f32 v143, v142, v143
	s_mov_b32 s71, 0x9bff000
	v_lshl_add_u64 v[180:181], v[146:147], 0, s[74:75]
	v_pack_b32_f16 v140, v153, v141
	v_cvt_f16_f32_e32 v145, v165
	v_alignbit_b32 v141, v144, v141, 16
	v_alignbit_b32 v142, v143, v144, 16
	v_add_co_u32_e32 v144, vcc, s71, v146
	v_cvt_f16_f32_e32 v146, v152
	v_cvt_pk_f16_f32 v138, v138, v139
	v_cvt_f16_f32_e32 v139, v151
	v_cvt_pk_f16_f32 v135, v134, v135
	v_cvt_pk_f16_f32 v137, v136, v137
	v_alignbit_b32 v143, v145, v143, 16
	v_addc_co_u32_e32 v145, vcc, 0, v147, vcc
	v_pack_b32_f16 v134, v146, v135
	v_alignbit_b32 v135, v138, v135, 16
	v_alignbit_b32 v136, v137, v138, 16
	v_alignbit_b32 v137, v139, v137, 16
	global_store_dwordx4 v[144:145], v[140:143], off offset:3840 nt
	global_store_dwordx4 v[180:181], v[134:137], off offset:64 nt
.LBB0_241:
	s_nop 1
	v_mov_b32_e32 v134, v111
	v_mov_b32_e32 v135, v112
	v_pk_mul_f32 v[140:141], v[134:135], v[174:175] op_sel_hi:[1,0]
	v_pk_mov_b32 v[134:135], v[112:113], v[106:107] op_sel:[1,0]
	v_pk_mov_b32 v[136:137], v[80:81], v[74:75] op_sel:[1,0]
	v_pk_mul_f32 v[144:145], v[134:135], v[174:175] op_sel_hi:[1,0]
	v_mov_b32_e32 v134, v107
	v_mov_b32_e32 v135, v108
	v_pk_mul_f32 v[142:143], v[134:135], v[174:175] op_sel_hi:[1,0]
	v_mov_b32_e32 v134, v79
	v_mov_b32_e32 v135, v80
	v_pk_mul_f32 v[138:139], v[136:137], v[174:175] op_sel_hi:[1,0]
	v_mov_b32_e32 v136, v75
	v_mov_b32_e32 v137, v76
	v_mul_f32_e32 v153, v110, v174
	v_mul_f32_e32 v165, v109, v174
	v_mul_f32_e32 v152, v78, v174
	v_pk_mul_f32 v[134:135], v[134:135], v[174:175] op_sel_hi:[1,0]
	v_pk_mul_f32 v[136:137], v[136:137], v[174:175] op_sel_hi:[1,0]
	v_mul_f32_e32 v151, v77, v174
	v_add_u32_e32 v146, 32, v164
	s_and_b64 vcc, exec, s[10:11]
	s_mov_b64 s[78:79], -1
	s_cbranch_vccnz .LBB0_251
	s_andn2_b64 vcc, exec, s[82:83]
	s_cbranch_vccnz .LBB0_248
	v_ashrrev_i32_e32 v147, 10, v146
	s_andn2_b64 vcc, exec, s[72:73]
	v_and_b32_e32 v147, 0xffffffc, v147
	s_cbranch_vccnz .LBB0_245
	v_add_u32_e32 v173, v147, v150
	v_lshl_add_u32 v180, v173, 4, v149
	v_ashrrev_i32_e32 v181, 31, v180
	v_lshlrev_b64 v[180:181], 13, v[180:181]
	s_movk_i32 s71, 0xfff
	v_and_or_b32 v173, v146, s71, v180
	v_lshl_or_b32 v180, s64, 12, v173
	s_nop 0
	v_lshl_add_u64 v[184:185], v[180:181], 4, s[16:17]
	v_cvt_pk_f16_f32 v183, v143, v165
	v_cvt_pk_f16_f32 v182, v145, v142
	v_cvt_pk_f16_f32 v181, v141, v144
	v_cvt_pk_f16_f32 v180, v153, v140
	global_store_dwordx4 v[184:185], v[180:183], off nt
	v_add_co_u32_e32 v184, vcc, 0x80000, v184
	s_nop 0
	v_cvt_pk_f16_f32 v183, v137, v151
	v_cvt_pk_f16_f32 v182, v139, v136
	v_cvt_pk_f16_f32 v181, v135, v138
	v_cvt_pk_f16_f32 v180, v152, v134
	v_addc_co_u32_e32 v185, vcc, 0, v185, vcc
	s_mov_b64 s[78:79], 0
	global_store_dwordx4 v[184:185], v[180:183], off nt

;     __device__ __forceinline__ void operator()(const f32x4 (&acc)[2][2][4][2], const pg8::Unit& u, int ui, LAS unsigned char* lds, int wr, int wc, int fr_, int fq_) const {
;     ...
;                 for (int m = 0; m < 4; ++m) {
;                     const int row = row0 + ai * 128 + m * 16;
;                     const float rs = rsv[ai * 4 + m];
;                     float v[2][8];
; #pragma unroll
;                     for (int bj = 0; bj < 2; ++bj)
; #pragma unroll
;                         for (int e = 0; e < 8; ++e) v[bj][e] = acc[ai][bj][m][e >> 2][e & 3] * rs;
;     ...
;                     } else {
;                         const int cg8 = 8 * (wc & 1) + fq;
;                         f16* p = Z + (((size_t)(((row >> 12) * 4 + (pn - 7)) * 16 + cg8) * 4096 + (row & 4095)) * 2 + (wc >> 1)) * 8;
;                         *(u32x4*)p = pack8(v[0]); *(u32x4*)(p + (size_t)4 * 4096 * 16) = pack8(v[1]);
.LBB0_253:
	s_nop 1
	v_mov_b32_e32 v134, v103
	v_mov_b32_e32 v135, v104
	v_pk_mul_f32 v[140:141], v[134:135], v[172:173] op_sel_hi:[1,0]
	v_pk_mov_b32 v[134:135], v[104:105], v[98:99] op_sel:[1,0]
	v_pk_mov_b32 v[136:137], v[72:73], v[66:67] op_sel:[1,0]
	v_pk_mul_f32 v[144:145], v[134:135], v[172:173] op_sel_hi:[1,0]
	v_mov_b32_e32 v134, v99
	v_mov_b32_e32 v135, v100
	v_pk_mul_f32 v[142:143], v[134:135], v[172:173] op_sel_hi:[1,0]
	v_mov_b32_e32 v134, v71
	v_mov_b32_e32 v135, v72
	v_pk_mul_f32 v[138:139], v[136:137], v[172:173] op_sel_hi:[1,0]
	v_mov_b32_e32 v136, v67
	v_mov_b32_e32 v137, v68
	v_mul_f32_e32 v153, v102, v172
	v_mul_f32_e32 v165, v101, v172
	v_mul_f32_e32 v152, v70, v172
	v_pk_mul_f32 v[134:135], v[134:135], v[172:173] op_sel_hi:[1,0]
	v_pk_mul_f32 v[136:137], v[136:137], v[172:173] op_sel_hi:[1,0]
	v_mul_f32_e32 v151, v69, v172
	v_add_u32_e32 v146, 48, v164
	s_and_b64 vcc, exec, s[10:11]
	s_mov_b64 s[78:79], -1
	s_cbranch_vccnz .LBB0_263
	s_andn2_b64 vcc, exec, s[82:83]
	s_cbranch_vccnz .LBB0_260
	v_ashrrev_i32_e32 v147, 10, v146
	s_andn2_b64 vcc, exec, s[72:73]
	v_and_b32_e32 v147, 0xffffffc, v147
	s_cbranch_vccnz .LBB0_257
	v_add_u32_e32 v173, v147, v150
	v_lshl_add_u32 v180, v173, 4, v149
	v_ashrrev_i32_e32 v181, 31, v180
	v_lshlrev_b64 v[180:181], 13, v[180:181]
	s_movk_i32 s71, 0xfff
	v_and_or_b32 v173, v146, s71, v180
	v_lshl_or_b32 v180, s64, 12, v173
	s_nop 0
	v_lshl_add_u64 v[184:185], v[180:181], 4, s[16:17]
	v_cvt_pk_f16_f32 v183, v143, v165
	v_cvt_pk_f16_f32 v182, v145, v142
	v_cvt_pk_f16_f32 v181, v141, v144
	v_cvt_pk_f16_f32 v180, v153, v140
	global_store_dwordx4 v[184:185], v[180:183], off nt
	v_add_co_u32_e32 v184, vcc, 0x80000, v184
	s_nop 0
	v_cvt_pk_f16_f32 v183, v137, v151
	v_cvt_pk_f16_f32 v182, v139, v136
	v_cvt_pk_f16_f32 v181, v135, v138
	v_cvt_pk_f16_f32 v180, v152, v134
	v_addc_co_u32_e32 v185, vcc, 0, v185, vcc
	s_mov_b64 s[78:79], 0
	global_store_dwordx4 v[184:185], v[180:183], off nt

; __device__ __forceinline__ float silu_f(float z) { return z * __builtin_amdgcn_rcpf(1.0f + __builtin_amdgcn_exp2f(-LOG2E * z)); }
;     __device__ __forceinline__ void operator()(const f32x4 (&acc)[2][2][4][2], const pg8::Unit& u, int ui, LAS unsigned char* lds, int wr, int wc, int fr_, int fq_) const {
;     ...
;                 for (int m = 0; m < 4; ++m) {
;                     const int row = row0 + ai * 128 + m * 16;
;                     const float rs = rsv[ai * 4 + m];
;                     float v[2][8];
; #pragma unroll
;                     for (int bj = 0; bj < 2; ++bj)
; #pragma unroll
;                         for (int e = 0; e < 8; ++e) v[bj][e] = acc[ai][bj][m][e >> 2][e & 3] * rs;
;                     if (pn == 2) {
;                         f16* p = V + (size_t)row * 128 + (wc - 2) * 64 + 8 * fq; *(u32x4*)p = pack8(v[0]); *(u32x4*)(p + 32) = pack8(v[1]);
;                     } else if (pn <= 4) {
; #pragma unroll
;                         for (int bj = 0; bj < 2; ++bj)
; #pragma unroll
;                             for (int e = 0; e < 8; ++e) v[bj][e] = silu_f(v[bj][e]);
;                         f16* p = GA + (size_t)row * 512 + (pn - 3) * 256 + wc * 64 + 8 * fq;
;                         *(u32x4*)p = pack8(v[0]); *(u32x4*)(p + 32) = pack8(v[1]);
;                     } else if (pn <= 6) {
; #pragma unroll
;                         for (int bj = 0; bj < 2; ++bj)
; #pragma unroll
;                             for (int e = 0; e < 8; ++e) v[bj][e] = silu_f(v[bj][e]);
;                         const int gq = 2 * (pn - 5) + (wc >> 1), cg8 = 8 * (wc & 1) + fq;
;                         f16* p = GF + ((size_t)(((row >> 12) * 4 + gq) * 16 + cg8) * 4096 + (row & 4095)) * 8;
;                         *(u32x4*)p = pack8(v[0]); *(u32x4*)(p + (size_t)4 * 4096 * 8) = pack8(v[1]);
;                     } else {
;                         const int cg8 = 8 * (wc & 1) + fq;
;                         f16* p = Z + (((size_t)(((row >> 12) * 4 + (pn - 7)) * 16 + cg8) * 4096 + (row & 4095)) * 2 + (wc >> 1)) * 8;
;                         *(u32x4*)p = pack8(v[0]); *(u32x4*)(p + (size_t)4 * 4096 * 16) = pack8(v[1]);
.LBB0_265:
	s_nop 1
	v_mov_b32_e32 v134, v63
	v_mov_b32_e32 v135, v64
	v_pk_mul_f32 v[140:141], v[134:135], v[170:171] op_sel_hi:[1,0]
	v_pk_mov_b32 v[134:135], v[64:65], v[58:59] op_sel:[1,0]
	v_pk_mov_b32 v[136:137], v[32:33], v[26:27] op_sel:[1,0]
	v_pk_mul_f32 v[146:147], v[134:135], v[170:171] op_sel_hi:[1,0]
	v_mov_b32_e32 v134, v59
	v_mov_b32_e32 v135, v60
	v_pk_mul_f32 v[142:143], v[134:135], v[170:171] op_sel_hi:[1,0]
	v_mov_b32_e32 v134, v31
	v_mov_b32_e32 v135, v32
	v_pk_mul_f32 v[138:139], v[136:137], v[170:171] op_sel_hi:[1,0]
	v_mov_b32_e32 v136, v27
	v_mov_b32_e32 v137, v28
	v_add_u32_e32 v144, 0x80, v164
	v_mul_f32_e32 v153, v62, v170
	v_mul_f32_e32 v165, v61, v170
	v_mul_f32_e32 v152, v30, v170
	v_pk_mul_f32 v[134:135], v[134:135], v[170:171] op_sel_hi:[1,0]
	v_pk_mul_f32 v[136:137], v[136:137], v[170:171] op_sel_hi:[1,0]
	v_mul_f32_e32 v151, v29, v170
	s_and_b64 vcc, exec, s[10:11]
	s_mov_b64 s[78:79], -1
	s_cbranch_vccnz .LBB0_275
	s_andn2_b64 vcc, exec, s[82:83]
	s_cbranch_vccnz .LBB0_272
	v_ashrrev_i32_e32 v145, 10, v144
	s_andn2_b64 vcc, exec, s[72:73]
	v_and_b32_e32 v145, 0xffffffc, v145
	s_cbranch_vccnz .LBB0_269
	v_add_u32_e32 v173, v145, v150
	v_lshl_add_u32 v180, v173, 4, v149
	v_ashrrev_i32_e32 v181, 31, v180
	v_lshlrev_b64 v[180:181], 13, v[180:181]
	s_movk_i32 s71, 0xfff
	v_and_or_b32 v173, v144, s71, v180
	v_lshl_or_b32 v180, s64, 12, v173
	s_nop 0
	v_lshl_add_u64 v[184:185], v[180:181], 4, s[16:17]
	v_cvt_pk_f16_f32 v183, v143, v165
	v_cvt_pk_f16_f32 v182, v147, v142
	v_cvt_pk_f16_f32 v181, v141, v146
	v_cvt_pk_f16_f32 v180, v153, v140
	global_store_dwordx4 v[184:185], v[180:183], off nt
	v_add_co_u32_e32 v184, vcc, 0x80000, v184
	s_nop 0
	v_cvt_pk_f16_f32 v183, v137, v151
	v_cvt_pk_f16_f32 v182, v139, v136
	v_cvt_pk_f16_f32 v181, v135, v138
	v_cvt_pk_f16_f32 v180, v152, v134
	v_addc_co_u32_e32 v185, vcc, 0, v185, vcc
	s_mov_b64 s[78:79], 0
	global_store_dwordx4 v[184:185], v[180:183], off nt
.LBB0_269:
	s_andn2_b64 vcc, exec, s[78:79]
	s_cbranch_vccnz .LBB0_271
	v_mul_f32_e32 v175, 0xbfb8aa3b, v140
	v_exp_f32_e32 v175, v175
	v_mul_f32_e32 v177, 0xbfb8aa3b, v141
	v_exp_f32_e32 v177, v177
	v_mul_f32_e32 v179, 0xbfb8aa3b, v146
	v_exp_f32_e32 v179, v179
	v_add_f32_e32 v175, 1.0, v175
	v_rcp_f32_e32 v180, v175
	v_add_f32_e32 v175, 1.0, v177
	v_mul_f32_e32 v177, 0xbfb8aa3b, v147
	v_rcp_f32_e32 v181, v175
	v_add_f32_e32 v175, 1.0, v179
	v_exp_f32_e32 v177, v177
	v_mul_f32_e32 v179, 0xbfb8aa3b, v142
	v_exp_f32_e32 v179, v179
	v_rcp_f32_e32 v182, v175
	v_add_f32_e32 v175, 1.0, v177
	v_mul_f32_e32 v177, 0xbfb8aa3b, v143
	v_rcp_f32_e32 v183, v175
	v_add_f32_e32 v175, 1.0, v179
	v_exp_f32_e32 v177, v177
	v_mul_f32_e32 v179, 0xbfb8aa3b, v165
	v_exp_f32_e32 v179, v179
	v_rcp_f32_e32 v184, v175
	v_add_f32_e32 v175, 1.0, v177
	v_rcp_f32_e32 v185, v175
	v_add_f32_e32 v175, 1.0, v179
	v_mul_f32_e32 v179, 0xbfb8aa3b, v134
	v_exp_f32_e32 v179, v179
	v_mul_f32_e32 v186, 0xbfb8aa3b, v135
	v_exp_f32_e32 v187, v186
	v_mul_f32_e32 v186, 0xbfb8aa3b, v138
	v_exp_f32_e32 v188, v186
	v_add_f32_e32 v179, 1.0, v179
	v_rcp_f32_e32 v186, v179
	v_add_f32_e32 v179, 1.0, v187
	v_rcp_f32_e32 v187, v179
	v_add_f32_e32 v179, 1.0, v188
	v_mul_f32_e32 v188, 0xbfb8aa3b, v139
	v_exp_f32_e32 v189, v188
	v_mul_f32_e32 v188, 0xbfb8aa3b, v136
	v_exp_f32_e32 v190, v188
	v_mul_f32_e32 v173, 0xbfb8aa3b, v153
	v_exp_f32_e32 v173, v173
	v_rcp_f32_e32 v188, v179
	v_add_f32_e32 v179, 1.0, v189
	v_rcp_f32_e32 v189, v179
	v_add_f32_e32 v179, 1.0, v190
	v_mul_f32_e32 v190, 0xbfb8aa3b, v137
	v_exp_f32_e32 v191, v190
	v_mul_f32_e32 v190, 0xbfb8aa3b, v151
	v_add_f32_e32 v173, 1.0, v173
	v_exp_f32_e32 v192, v190
	v_rcp_f32_e32 v173, v173
	v_mul_f32_e32 v177, 0xbfb8aa3b, v152
	v_exp_f32_e32 v177, v177
	v_rcp_f32_e32 v190, v179
	v_add_f32_e32 v179, 1.0, v191
	v_add_u32_e32 v145, s67, v145
	v_rcp_f32_e32 v191, v179
	v_add_f32_e32 v179, 1.0, v192
	v_lshl_add_u32 v192, v145, 4, v149
	v_lshlrev_b32_e32 v145, 4, v144
	v_pk_mul_f32 v[180:181], v[140:141], v[180:181]
	v_rcp_f32_e32 v175, v175
	v_and_b32_e32 v194, 0xfff0, v145
	v_fma_mixlo_f16 v145, v153, v173, 0
	v_cvt_pk_f16_f32 v173, v180, v181
	v_pk_mul_f32 v[182:183], v[146:147], v[182:183]
	v_add_f32_e32 v177, 1.0, v177
	v_ashrrev_i32_e32 v193, 31, v192
	v_readlane_b32 s74, v254, 6
	v_pack_b32_f16 v180, v145, v173
	v_cvt_pk_f16_f32 v145, v182, v183
	v_pk_mul_f32 v[182:183], v[142:143], v[184:185]
	v_rcp_f32_e32 v177, v177
	v_lshlrev_b64 v[192:193], 16, v[192:193]
	v_readlane_b32 s75, v254, 7
	v_alignbit_b32 v181, v145, v173, 16
	v_cvt_pk_f16_f32 v173, v182, v183
	v_lshl_add_u64 v[192:193], s[74:75], 0, v[192:193]
	v_lshrrev_b32_e32 v183, 16, v173
	v_lshl_add_u64 v[192:193], v[192:193], 0, v[194:195]
	v_alignbit_b32 v182, v173, v145, 16
	v_fma_mixhi_f16 v183, v165, v175, 0
	global_store_dwordx4 v[192:193], v[180:183], off nt
	v_rcp_f32_e32 v179, v179
	v_fma_mixlo_f16 v145, v152, v177, 0
	v_pk_mul_f32 v[180:181], v[134:135], v[186:187]
	v_pk_mul_f32 v[182:183], v[138:139], v[188:189]
	v_cvt_pk_f16_f32 v173, v180, v181
	v_pack_b32_f16 v180, v145, v173
	v_cvt_pk_f16_f32 v145, v182, v183
	v_pk_mul_f32 v[182:183], v[136:137], v[190:191]
	v_alignbit_b32 v181, v145, v173, 16
	v_cvt_pk_f16_f32 v173, v182, v183
	v_lshrrev_b32_e32 v183, 16, v173
	v_add_co_u32_e32 v184, vcc, 0x40000, v192
	v_alignbit_b32 v182, v173, v145, 16
	v_fma_mixhi_f16 v183, v151, v179, 0
	v_addc_co_u32_e32 v185, vcc, 0, v193, vcc
	global_store_dwordx4 v[184:185], v[180:183], off nt

; __device__ __forceinline__ float silu_f(float z) { return z * __builtin_amdgcn_rcpf(1.0f + __builtin_amdgcn_exp2f(-LOG2E * z)); }
;     __device__ __forceinline__ void operator()(const f32x4 (&acc)[2][2][4][2], const pg8::Unit& u, int ui, LAS unsigned char* lds, int wr, int wc, int fr_, int fq_) const {
;     ...
;                     } else if (pn <= 4) {
; #pragma unroll
;                         for (int bj = 0; bj < 2; ++bj)
; #pragma unroll
;                             for (int e = 0; e < 8; ++e) v[bj][e] = silu_f(v[bj][e]);
;                         f16* p = GA + (size_t)row * 512 + (pn - 3) * 256 + wc * 64 + 8 * fq;
;                         *(u32x4*)p = pack8(v[0]); *(u32x4*)(p + 32) = pack8(v[1]);
.LBB0_272:
	s_andn2_b64 vcc, exec, s[78:79]
	s_cbranch_vccnz .LBB0_274
	v_mul_f32_e32 v145, 0xbfb8aa3b, v153
	v_exp_f32_e32 v145, v145
	v_mul_f32_e32 v173, 0xbfb8aa3b, v140
	v_exp_f32_e32 v173, v173
	v_mul_f32_e32 v177, 0xbfb8aa3b, v146
	v_add_f32_e32 v145, 1.0, v145
	v_rcp_f32_e32 v175, v145
	v_mul_f32_e32 v145, 0xbfb8aa3b, v141
	v_exp_f32_e32 v145, v145
	v_exp_f32_e32 v177, v177
	v_add_f32_e32 v173, 1.0, v173
	v_rcp_f32_e32 v180, v173
	v_add_f32_e32 v145, 1.0, v145
	v_mul_f32_e32 v173, 0xbfb8aa3b, v147
	v_rcp_f32_e32 v181, v145
	v_add_f32_e32 v145, 1.0, v177
	v_exp_f32_e32 v173, v173
	v_mul_f32_e32 v177, 0xbfb8aa3b, v142
	v_exp_f32_e32 v177, v177
	v_rcp_f32_e32 v182, v145
	v_add_f32_e32 v145, 1.0, v173
	v_mul_f32_e32 v173, 0xbfb8aa3b, v143
	v_rcp_f32_e32 v183, v145
	v_add_f32_e32 v145, 1.0, v177
	v_exp_f32_e32 v173, v173
	v_mul_f32_e32 v177, 0xbfb8aa3b, v165
	v_exp_f32_e32 v177, v177
	v_rcp_f32_e32 v184, v145
	v_add_f32_e32 v145, 1.0, v173
	v_mul_f32_e32 v173, 0xbfb8aa3b, v152
	v_rcp_f32_e32 v185, v145
	v_add_f32_e32 v145, 1.0, v177
	v_exp_f32_e32 v173, v173
	v_mul_f32_e32 v177, 0xbfb8aa3b, v134
	v_exp_f32_e32 v177, v177
	v_rcp_f32_e32 v179, v145
	v_add_f32_e32 v145, 1.0, v173
	v_rcp_f32_e32 v173, v145
	v_add_f32_e32 v145, 1.0, v177
	v_mul_f32_e32 v177, 0xbfb8aa3b, v135
	v_exp_f32_e32 v177, v177
	v_mul_f32_e32 v186, 0xbfb8aa3b, v138
	v_exp_f32_e32 v188, v186
	v_rcp_f32_e32 v186, v145
	v_add_f32_e32 v145, 1.0, v177
	v_mul_f32_e32 v177, 0xbfb8aa3b, v139
	v_rcp_f32_e32 v187, v145
	v_add_f32_e32 v145, 1.0, v188
	v_exp_f32_e32 v177, v177
	v_mul_f32_e32 v188, 0xbfb8aa3b, v136
	v_exp_f32_e32 v190, v188
	v_rcp_f32_e32 v188, v145
	v_add_f32_e32 v145, 1.0, v177
	v_mul_f32_e32 v177, 0xbfb8aa3b, v137
	v_rcp_f32_e32 v189, v145
	v_add_f32_e32 v145, 1.0, v190
	v_exp_f32_e32 v177, v177
	v_mul_f32_e32 v190, 0xbfb8aa3b, v151
	v_exp_f32_e32 v192, v190
	v_rcp_f32_e32 v190, v145
	v_add_f32_e32 v145, 1.0, v177
	v_rcp_f32_e32 v191, v145
	v_add_f32_e32 v145, 1.0, v192
	v_rcp_f32_e32 v177, v145
	v_ashrrev_i32_e32 v145, 31, v144
	v_pk_mul_f32 v[180:181], v[140:141], v[180:181]
	v_lshlrev_b64 v[192:193], 10, v[144:145]
	v_fma_mixlo_f16 v145, v153, v175, 0
	v_cvt_pk_f16_f32 v175, v180, v181
	v_pk_mul_f32 v[182:183], v[146:147], v[182:183]
	v_pack_b32_f16 v180, v145, v175
	v_cvt_pk_f16_f32 v145, v182, v183
	v_pk_mul_f32 v[182:183], v[142:143], v[184:185]
	v_alignbit_b32 v181, v145, v175, 16
	v_cvt_pk_f16_f32 v175, v182, v183
	v_lshrrev_b32_e32 v183, 16, v175
	v_lshl_add_u64 v[192:193], v[132:133], 0, v[192:193]
	v_alignbit_b32 v182, v175, v145, 16
	v_fma_mixhi_f16 v183, v165, v179, 0
	global_store_dwordx4 v[192:193], v[180:183], off offset:-1536 nt
	v_fma_mixlo_f16 v145, v152, v173, 0
	s_nop 0
	v_pk_mul_f32 v[180:181], v[134:135], v[186:187]
	v_pk_mul_f32 v[182:183], v[138:139], v[188:189]
	v_cvt_pk_f16_f32 v173, v180, v181
	v_pack_b32_f16 v180, v145, v173
	v_cvt_pk_f16_f32 v145, v182, v183
	v_pk_mul_f32 v[182:183], v[136:137], v[190:191]
	v_alignbit_b32 v181, v145, v173, 16
	v_cvt_pk_f16_f32 v173, v182, v183
	v_lshrrev_b32_e32 v183, 16, v173
	v_alignbit_b32 v182, v173, v145, 16
	v_fma_mixhi_f16 v183, v151, v177, 0
	global_store_dwordx4 v[192:193], v[180:183], off offset:-1472 nt

; __device__ __forceinline__ float silu_f(float z) { return z * __builtin_amdgcn_rcpf(1.0f + __builtin_amdgcn_exp2f(-LOG2E * z)); }
;     __device__ __forceinline__ void operator()(const f32x4 (&acc)[2][2][4][2], const pg8::Unit& u, int ui, LAS unsigned char* lds, int wr, int wc, int fr_, int fq_) const {
;     ...
;                     if (pn == 2) {
;                         f16* p = V + (size_t)row * 128 + (wc - 2) * 64 + 8 * fq; *(u32x4*)p = pack8(v[0]); *(u32x4*)(p + 32) = pack8(v[1]);
;                     } else if (pn <= 4) {
; #pragma unroll
;                         for (int bj = 0; bj < 2; ++bj)
; #pragma unroll
;                             for (int e = 0; e < 8; ++e) v[bj][e] = silu_f(v[bj][e]);
;                         f16* p = GA + (size_t)row * 512 + (pn - 3) * 256 + wc * 64 + 8 * fq;
;                         *(u32x4*)p = pack8(v[0]); *(u32x4*)(p + 32) = pack8(v[1]);
;                     } else if (pn <= 6) {
; #pragma unroll
;                         for (int bj = 0; bj < 2; ++bj)
; #pragma unroll
;                             for (int e = 0; e < 8; ++e) v[bj][e] = silu_f(v[bj][e]);
;                         const int gq = 2 * (pn - 5) + (wc >> 1), cg8 = 8 * (wc & 1) + fq;
;                         f16* p = GF + ((size_t)(((row >> 12) * 4 + gq) * 16 + cg8) * 4096 + (row & 4095)) * 8;
;                         *(u32x4*)p = pack8(v[0]); *(u32x4*)(p + (size_t)4 * 4096 * 8) = pack8(v[1]);
;                     } else {
;                         const int cg8 = 8 * (wc & 1) + fq;
;                         f16* p = Z + (((size_t)(((row >> 12) * 4 + (pn - 7)) * 16 + cg8) * 4096 + (row & 4095)) * 2 + (wc >> 1)) * 8;
;                         *(u32x4*)p = pack8(v[0]); *(u32x4*)(p + (size_t)4 * 4096 * 16) = pack8(v[1]);
.LBB0_275:
	s_andn2_b64 vcc, exec, s[78:79]
	s_cbranch_vccnz .LBB0_277
	v_cvt_f16_f32_e32 v153, v153
	v_ashrrev_i32_e32 v145, 31, v144
	v_cvt_pk_f16_f32 v141, v140, v141
	v_cvt_pk_f16_f32 v146, v146, v147
	v_cvt_pk_f16_f32 v143, v142, v143
	v_lshlrev_b64 v[144:145], 8, v[144:145]
	v_pack_b32_f16 v140, v153, v141
	v_cvt_f16_f32_e32 v147, v165
	v_alignbit_b32 v141, v146, v141, 16
	v_alignbit_b32 v142, v143, v146, 16
	v_cvt_f16_f32_e32 v146, v152
	v_cvt_pk_f16_f32 v138, v138, v139
	v_cvt_f16_f32_e32 v139, v151
	v_lshl_add_u64 v[144:145], s[80:81], 0, v[144:145]
	v_lshl_add_u64 v[144:145], v[130:131], 1, v[144:145]
	s_mov_b64 s[74:75], 0x9bfff00
	s_mov_b32 s71, 0x9bff000
	v_lshl_add_u64 v[180:181], v[144:145], 0, s[74:75]
	v_add_co_u32_e32 v144, vcc, s71, v144
	v_cvt_pk_f16_f32 v135, v134, v135
	v_cvt_pk_f16_f32 v137, v136, v137
	v_alignbit_b32 v143, v147, v143, 16
	v_addc_co_u32_e32 v145, vcc, 0, v145, vcc
	v_pack_b32_f16 v134, v146, v135
	v_alignbit_b32 v135, v138, v135, 16
	v_alignbit_b32 v136, v137, v138, 16
	v_alignbit_b32 v137, v139, v137, 16
	global_store_dwordx4 v[144:145], v[140:143], off offset:3840 nt
	global_store_dwordx4 v[180:181], v[134:137], off offset:64 nt
.LBB0_277:
	s_nop 1
	v_mov_b32_e32 v134, v55
	v_mov_b32_e32 v135, v56
	v_pk_mul_f32 v[140:141], v[134:135], v[168:169] op_sel_hi:[1,0]
	v_pk_mov_b32 v[134:135], v[56:57], v[50:51] op_sel:[1,0]
	v_pk_mov_b32 v[136:137], v[24:25], v[18:19] op_sel:[1,0]
	v_pk_mul_f32 v[144:145], v[134:135], v[168:169] op_sel_hi:[1,0]
	v_mov_b32_e32 v134, v51
	v_mov_b32_e32 v135, v52
	v_pk_mul_f32 v[142:143], v[134:135], v[168:169] op_sel_hi:[1,0]
	v_mov_b32_e32 v134, v23
	v_mov_b32_e32 v135, v24
	v_pk_mul_f32 v[138:139], v[136:137], v[168:169] op_sel_hi:[1,0]
	v_mov_b32_e32 v136, v19
	v_mov_b32_e32 v137, v20
	v_mul_f32_e32 v153, v54, v168
	v_mul_f32_e32 v165, v53, v168
	v_mul_f32_e32 v152, v22, v168
	v_pk_mul_f32 v[134:135], v[134:135], v[168:169] op_sel_hi:[1,0]
	v_pk_mul_f32 v[136:137], v[136:137], v[168:169] op_sel_hi:[1,0]
	v_mul_f32_e32 v151, v21, v168
	v_add_u32_e32 v146, 0x90, v164
	s_and_b64 vcc, exec, s[10:11]
	s_mov_b64 s[78:79], -1
	s_cbranch_vccnz .LBB0_287
	s_andn2_b64 vcc, exec, s[82:83]
	s_cbranch_vccnz .LBB0_284
	v_ashrrev_i32_e32 v147, 10, v146
	s_andn2_b64 vcc, exec, s[72:73]
	v_and_b32_e32 v147, 0xffffffc, v147
	s_cbranch_vccnz .LBB0_281
	v_add_u32_e32 v173, v147, v150
	v_lshl_add_u32 v180, v173, 4, v149
	v_ashrrev_i32_e32 v181, 31, v180
	v_lshlrev_b64 v[180:181], 13, v[180:181]
	s_movk_i32 s71, 0xfff
	v_and_or_b32 v173, v146, s71, v180
	v_lshl_or_b32 v180, s64, 12, v173
	s_nop 0
	v_lshl_add_u64 v[184:185], v[180:181], 4, s[16:17]
	v_cvt_pk_f16_f32 v183, v143, v165
	v_cvt_pk_f16_f32 v182, v145, v142
	v_cvt_pk_f16_f32 v181, v141, v144
	v_cvt_pk_f16_f32 v180, v153, v140
	global_store_dwordx4 v[184:185], v[180:183], off nt
	v_add_co_u32_e32 v184, vcc, 0x80000, v184
	s_nop 0
	v_cvt_pk_f16_f32 v183, v137, v151
	v_cvt_pk_f16_f32 v182, v139, v136
	v_cvt_pk_f16_f32 v181, v135, v138
	v_cvt_pk_f16_f32 v180, v152, v134
	v_addc_co_u32_e32 v185, vcc, 0, v185, vcc
	s_mov_b64 s[78:79], 0
	global_store_dwordx4 v[184:185], v[180:183], off nt

;     __device__ __forceinline__ void operator()(const f32x4 (&acc)[2][2][4][2], const pg8::Unit& u, int ui, LAS unsigned char* lds, int wr, int wc, int fr_, int fq_) const {
;     ...
;                 for (int m = 0; m < 4; ++m) {
;                     const int row = row0 + ai * 128 + m * 16;
;                     const float rs = rsv[ai * 4 + m];
;                     float v[2][8];
; #pragma unroll
;                     for (int bj = 0; bj < 2; ++bj)
; #pragma unroll
;                         for (int e = 0; e < 8; ++e) v[bj][e] = acc[ai][bj][m][e >> 2][e & 3] * rs;
;     ...
;                     } else {
;                         const int cg8 = 8 * (wc & 1) + fq;
;                         f16* p = Z + (((size_t)(((row >> 12) * 4 + (pn - 7)) * 16 + cg8) * 4096 + (row & 4095)) * 2 + (wc >> 1)) * 8;
;                         *(u32x4*)p = pack8(v[0]); *(u32x4*)(p + (size_t)4 * 4096 * 16) = pack8(v[1]);
.LBB0_289:
	s_nop 1
	v_mov_b32_e32 v134, v47
	v_mov_b32_e32 v135, v48
	v_pk_mul_f32 v[140:141], v[134:135], v[166:167] op_sel_hi:[1,0]
	v_pk_mov_b32 v[134:135], v[48:49], v[42:43] op_sel:[1,0]
	v_pk_mov_b32 v[136:137], v[16:17], v[10:11] op_sel:[1,0]
	v_pk_mul_f32 v[144:145], v[134:135], v[166:167] op_sel_hi:[1,0]
	v_mov_b32_e32 v134, v43
	v_mov_b32_e32 v135, v44
	v_pk_mul_f32 v[142:143], v[134:135], v[166:167] op_sel_hi:[1,0]
	v_mov_b32_e32 v134, v15
	v_mov_b32_e32 v135, v16
	v_pk_mul_f32 v[138:139], v[136:137], v[166:167] op_sel_hi:[1,0]
	v_mov_b32_e32 v136, v11
	v_mov_b32_e32 v137, v12
	v_mul_f32_e32 v153, v46, v166
	v_mul_f32_e32 v165, v45, v166
	v_mul_f32_e32 v152, v14, v166
	v_pk_mul_f32 v[134:135], v[134:135], v[166:167] op_sel_hi:[1,0]
	v_pk_mul_f32 v[136:137], v[136:137], v[166:167] op_sel_hi:[1,0]
	v_mul_f32_e32 v151, v13, v166
	v_add_u32_e32 v146, 0xa0, v164
	s_and_b64 vcc, exec, s[10:11]
	s_mov_b64 s[78:79], -1
	s_cbranch_vccnz .LBB0_299
	s_andn2_b64 vcc, exec, s[82:83]
	s_cbranch_vccnz .LBB0_296
	v_ashrrev_i32_e32 v147, 10, v146
	s_andn2_b64 vcc, exec, s[72:73]
	v_and_b32_e32 v147, 0xffffffc, v147
	s_cbranch_vccnz .LBB0_293
	v_add_u32_e32 v173, v147, v150
	v_lshl_add_u32 v180, v173, 4, v149
	v_ashrrev_i32_e32 v181, 31, v180
	v_lshlrev_b64 v[180:181], 13, v[180:181]
	s_movk_i32 s71, 0xfff
	v_and_or_b32 v173, v146, s71, v180
	v_lshl_or_b32 v180, s64, 12, v173
	s_nop 0
	v_lshl_add_u64 v[184:185], v[180:181], 4, s[16:17]
	v_cvt_pk_f16_f32 v183, v143, v165
	v_cvt_pk_f16_f32 v182, v145, v142
	v_cvt_pk_f16_f32 v181, v141, v144
	v_cvt_pk_f16_f32 v180, v153, v140
	global_store_dwordx4 v[184:185], v[180:183], off nt
	v_add_co_u32_e32 v184, vcc, 0x80000, v184
	s_nop 0
	v_cvt_pk_f16_f32 v183, v137, v151
	v_cvt_pk_f16_f32 v182, v139, v136
	v_cvt_pk_f16_f32 v181, v135, v138
	v_cvt_pk_f16_f32 v180, v152, v134
	v_addc_co_u32_e32 v185, vcc, 0, v185, vcc
	s_mov_b64 s[78:79], 0
	global_store_dwordx4 v[184:185], v[180:183], off nt

; __device__ __forceinline__ float silu_f(float z) { return z * __builtin_amdgcn_rcpf(1.0f + __builtin_amdgcn_exp2f(-LOG2E * z)); }
;     __device__ __forceinline__ void operator()(const f32x4 (&acc)[2][2][4][2], const pg8::Unit& u, int ui, LAS unsigned char* lds, int wr, int wc, int fr_, int fq_) const {
;     ...
;                 for (int m = 0; m < 4; ++m) {
;                     const int row = row0 + ai * 128 + m * 16;
;                     const float rs = rsv[ai * 4 + m];
;                     float v[2][8];
; #pragma unroll
;                     for (int bj = 0; bj < 2; ++bj)
; #pragma unroll
;                         for (int e = 0; e < 8; ++e) v[bj][e] = acc[ai][bj][m][e >> 2][e & 3] * rs;
;                     if (pn == 2) {
;                         f16* p = V + (size_t)row * 128 + (wc - 2) * 64 + 8 * fq; *(u32x4*)p = pack8(v[0]); *(u32x4*)(p + 32) = pack8(v[1]);
;                     } else if (pn <= 4) {
; #pragma unroll
;                         for (int bj = 0; bj < 2; ++bj)
; #pragma unroll
;                             for (int e = 0; e < 8; ++e) v[bj][e] = silu_f(v[bj][e]);
;                         f16* p = GA + (size_t)row * 512 + (pn - 3) * 256 + wc * 64 + 8 * fq;
;                         *(u32x4*)p = pack8(v[0]); *(u32x4*)(p + 32) = pack8(v[1]);
;                     } else if (pn <= 6) {
; #pragma unroll
;                         for (int bj = 0; bj < 2; ++bj)
; #pragma unroll
;                             for (int e = 0; e < 8; ++e) v[bj][e] = silu_f(v[bj][e]);
;                         const int gq = 2 * (pn - 5) + (wc >> 1), cg8 = 8 * (wc & 1) + fq;
;                         f16* p = GF + ((size_t)(((row >> 12) * 4 + gq) * 16 + cg8) * 4096 + (row & 4095)) * 8;
;                         *(u32x4*)p = pack8(v[0]); *(u32x4*)(p + (size_t)4 * 4096 * 8) = pack8(v[1]);
;                     } else {
;                         const int cg8 = 8 * (wc & 1) + fq;
;                         f16* p = Z + (((size_t)(((row >> 12) * 4 + (pn - 7)) * 16 + cg8) * 4096 + (row & 4095)) * 2 + (wc >> 1)) * 8;
;                         *(u32x4*)p = pack8(v[0]); *(u32x4*)(p + (size_t)4 * 4096 * 16) = pack8(v[1]);
.LBB0_301:
	s_nop 1
	v_mov_b32_e32 v134, v39
	v_mov_b32_e32 v135, v40
	v_pk_mul_f32 v[140:141], v[134:135], v[162:163] op_sel_hi:[1,0]
	v_pk_mov_b32 v[134:135], v[40:41], v[34:35] op_sel:[1,0]
	v_pk_mov_b32 v[136:137], v[8:9], v[2:3] op_sel:[1,0]
	v_pk_mul_f32 v[144:145], v[134:135], v[162:163] op_sel_hi:[1,0]
	v_mov_b32_e32 v134, v35
	v_mov_b32_e32 v135, v36
	v_pk_mul_f32 v[142:143], v[134:135], v[162:163] op_sel_hi:[1,0]
	v_mov_b32_e32 v134, v7
	v_mov_b32_e32 v135, v8
	v_pk_mul_f32 v[138:139], v[136:137], v[162:163] op_sel_hi:[1,0]
	v_mov_b32_e32 v136, v3
	v_mov_b32_e32 v137, v4
	v_mul_f32_e32 v153, v38, v162
	v_mul_f32_e32 v165, v37, v162
	v_mul_f32_e32 v152, v6, v162
	v_pk_mul_f32 v[134:135], v[134:135], v[162:163] op_sel_hi:[1,0]
	v_pk_mul_f32 v[136:137], v[136:137], v[162:163] op_sel_hi:[1,0]
	v_mul_f32_e32 v151, v5, v162
	v_add_u32_e32 v146, 0xb0, v164
	s_and_b64 vcc, exec, s[10:11]
	s_mov_b64 s[10:11], -1
	s_cbranch_vccnz .LBB0_311
	s_andn2_b64 vcc, exec, s[82:83]
	s_cbranch_vccnz .LBB0_308
	v_ashrrev_i32_e32 v147, 10, v146
	s_andn2_b64 vcc, exec, s[72:73]
	v_and_b32_e32 v147, 0xffffffc, v147
	s_cbranch_vccnz .LBB0_305
	v_add_u32_e32 v150, v147, v150
	v_lshl_add_u32 v180, v150, 4, v149
	v_ashrrev_i32_e32 v181, 31, v180
	v_lshlrev_b64 v[180:181], 13, v[180:181]
	s_movk_i32 s10, 0xfff
	v_and_or_b32 v150, v146, s10, v180
	v_lshl_or_b32 v180, s64, 12, v150
	s_nop 0
	v_lshl_add_u64 v[184:185], v[180:181], 4, s[16:17]
	v_cvt_pk_f16_f32 v183, v143, v165
	v_cvt_pk_f16_f32 v182, v145, v142
	v_cvt_pk_f16_f32 v181, v141, v144
	v_cvt_pk_f16_f32 v180, v153, v140
	global_store_dwordx4 v[184:185], v[180:183], off nt
	v_add_co_u32_e32 v184, vcc, 0x80000, v184
	s_nop 0
	v_cvt_pk_f16_f32 v183, v137, v151
	v_cvt_pk_f16_f32 v182, v139, v136
	v_cvt_pk_f16_f32 v181, v135, v138
	v_cvt_pk_f16_f32 v180, v152, v134
	v_addc_co_u32_e32 v185, vcc, 0, v185, vcc
	s_mov_b64 s[10:11], 0
	global_store_dwordx4 v[184:185], v[180:183], off nt
.LBB0_305:
	s_andn2_b64 vcc, exec, s[10:11]
	s_cbranch_vccnz .LBB0_307
	v_mul_f32_e32 v173, 0xbfb8aa3b, v140
	v_exp_f32_e32 v173, v173
	v_mul_f32_e32 v175, 0xbfb8aa3b, v141
	v_exp_f32_e32 v175, v175
	v_mul_f32_e32 v177, 0xbfb8aa3b, v144
	v_exp_f32_e32 v177, v177
	v_add_f32_e32 v173, 1.0, v173
	v_rcp_f32_e32 v180, v173
	v_add_f32_e32 v173, 1.0, v175
	v_mul_f32_e32 v175, 0xbfb8aa3b, v145
	v_rcp_f32_e32 v181, v173
	v_add_f32_e32 v173, 1.0, v177
	v_exp_f32_e32 v175, v175
	v_mul_f32_e32 v177, 0xbfb8aa3b, v142
	v_exp_f32_e32 v177, v177
	v_rcp_f32_e32 v182, v173
	v_add_f32_e32 v173, 1.0, v175
	v_mul_f32_e32 v175, 0xbfb8aa3b, v143
	v_rcp_f32_e32 v183, v173
	v_add_f32_e32 v173, 1.0, v177
	v_exp_f32_e32 v175, v175
	v_mul_f32_e32 v177, 0xbfb8aa3b, v165
	v_exp_f32_e32 v177, v177
	v_rcp_f32_e32 v184, v173
	v_add_f32_e32 v173, 1.0, v175
	v_rcp_f32_e32 v185, v173
	v_add_f32_e32 v173, 1.0, v177
	v_mul_f32_e32 v177, 0xbfb8aa3b, v134
	v_exp_f32_e32 v177, v177
	v_mul_f32_e32 v179, 0xbfb8aa3b, v135
	v_exp_f32_e32 v179, v179
	v_mul_f32_e32 v186, 0xbfb8aa3b, v138
	v_exp_f32_e32 v188, v186
	v_add_f32_e32 v177, 1.0, v177
	v_rcp_f32_e32 v186, v177
	v_add_f32_e32 v177, 1.0, v179
	v_mul_f32_e32 v179, 0xbfb8aa3b, v139
	v_rcp_f32_e32 v187, v177
	v_add_f32_e32 v177, 1.0, v188
	v_exp_f32_e32 v179, v179
	v_mul_f32_e32 v188, 0xbfb8aa3b, v136
	v_mul_f32_e32 v150, 0xbfb8aa3b, v153
	v_exp_f32_e32 v190, v188
	v_exp_f32_e32 v150, v150
	v_rcp_f32_e32 v188, v177
	v_add_f32_e32 v177, 1.0, v179
	v_mul_f32_e32 v179, 0xbfb8aa3b, v137
	v_rcp_f32_e32 v189, v177
	v_add_f32_e32 v177, 1.0, v190
	v_exp_f32_e32 v179, v179
	v_mul_f32_e32 v190, 0xbfb8aa3b, v151
	v_add_f32_e32 v150, 1.0, v150
	v_exp_f32_e32 v192, v190
	v_rcp_f32_e32 v150, v150
	v_mul_f32_e32 v175, 0xbfb8aa3b, v152
	v_exp_f32_e32 v175, v175
	v_rcp_f32_e32 v190, v177
	v_add_f32_e32 v177, 1.0, v179
	v_add_u32_e32 v147, s67, v147
	v_rcp_f32_e32 v191, v177
	v_add_f32_e32 v177, 1.0, v192
	v_lshl_add_u32 v192, v147, 4, v149
	v_lshlrev_b32_e32 v147, 4, v146
	v_pk_mul_f32 v[180:181], v[140:141], v[180:181]
	v_rcp_f32_e32 v173, v173
	v_and_b32_e32 v194, 0xfff0, v147
	v_fma_mixlo_f16 v147, v153, v150, 0
	v_cvt_pk_f16_f32 v149, v180, v181
	v_pk_mul_f32 v[182:183], v[144:145], v[182:183]
	v_add_f32_e32 v175, 1.0, v175
	v_ashrrev_i32_e32 v193, 31, v192
	v_readlane_b32 s10, v254, 6
	v_pack_b32_f16 v180, v147, v149
	v_cvt_pk_f16_f32 v147, v182, v183
	v_pk_mul_f32 v[182:183], v[142:143], v[184:185]
	v_rcp_f32_e32 v175, v175
	v_lshlrev_b64 v[192:193], 16, v[192:193]
	v_readlane_b32 s11, v254, 7
	v_alignbit_b32 v181, v147, v149, 16
	v_cvt_pk_f16_f32 v149, v182, v183
	v_lshl_add_u64 v[192:193], s[10:11], 0, v[192:193]
	v_lshrrev_b32_e32 v183, 16, v149
	v_lshl_add_u64 v[192:193], v[192:193], 0, v[194:195]
	v_alignbit_b32 v182, v149, v147, 16
	v_fma_mixhi_f16 v183, v165, v173, 0
	global_store_dwordx4 v[192:193], v[180:183], off nt
	v_rcp_f32_e32 v177, v177
	v_fma_mixlo_f16 v147, v152, v175, 0
	v_pk_mul_f32 v[180:181], v[134:135], v[186:187]
	v_pk_mul_f32 v[182:183], v[138:139], v[188:189]
	v_cvt_pk_f16_f32 v149, v180, v181
	v_pack_b32_f16 v180, v147, v149
	v_cvt_pk_f16_f32 v147, v182, v183
	v_pk_mul_f32 v[182:183], v[136:137], v[190:191]
	v_alignbit_b32 v181, v147, v149, 16
	v_cvt_pk_f16_f32 v149, v182, v183
	v_lshrrev_b32_e32 v183, 16, v149
	v_add_co_u32_e32 v184, vcc, 0x40000, v192
	v_alignbit_b32 v182, v149, v147, 16
	v_fma_mixhi_f16 v183, v151, v177, 0
	v_addc_co_u32_e32 v185, vcc, 0, v193, vcc
	global_store_dwordx4 v[184:185], v[180:183], off nt

; __device__ __forceinline__ float silu_f(float z) { return z * __builtin_amdgcn_rcpf(1.0f + __builtin_amdgcn_exp2f(-LOG2E * z)); }
;     __device__ __forceinline__ void operator()(const f32x4 (&acc)[2][2][4][2], const pg8::Unit& u, int ui, LAS unsigned char* lds, int wr, int wc, int fr_, int fq_) const {
;     ...
;                     } else if (pn <= 4) {
; #pragma unroll
;                         for (int bj = 0; bj < 2; ++bj)
; #pragma unroll
;                             for (int e = 0; e < 8; ++e) v[bj][e] = silu_f(v[bj][e]);
;                         f16* p = GA + (size_t)row * 512 + (pn - 3) * 256 + wc * 64 + 8 * fq;
;                         *(u32x4*)p = pack8(v[0]); *(u32x4*)(p + 32) = pack8(v[1]);
.LBB0_308:
	s_andn2_b64 vcc, exec, s[10:11]
	s_cbranch_vccnz .LBB0_310
	v_mul_f32_e32 v147, 0xbfb8aa3b, v153
	v_exp_f32_e32 v147, v147
	v_mul_f32_e32 v149, 0xbfb8aa3b, v140
	v_exp_f32_e32 v149, v149
	v_mul_f32_e32 v173, 0xbfb8aa3b, v144
	v_add_f32_e32 v147, 1.0, v147
	v_rcp_f32_e32 v150, v147
	v_mul_f32_e32 v147, 0xbfb8aa3b, v141
	v_exp_f32_e32 v147, v147
	v_exp_f32_e32 v173, v173
	v_add_f32_e32 v149, 1.0, v149
	v_rcp_f32_e32 v180, v149
	v_add_f32_e32 v147, 1.0, v147
	v_mul_f32_e32 v149, 0xbfb8aa3b, v145
	v_rcp_f32_e32 v181, v147
	v_add_f32_e32 v147, 1.0, v173
	v_exp_f32_e32 v149, v149
	v_mul_f32_e32 v173, 0xbfb8aa3b, v142
	v_exp_f32_e32 v173, v173
	v_rcp_f32_e32 v182, v147
	v_add_f32_e32 v147, 1.0, v149
	v_mul_f32_e32 v149, 0xbfb8aa3b, v143
	v_rcp_f32_e32 v183, v147
	v_add_f32_e32 v147, 1.0, v173
	v_exp_f32_e32 v149, v149
	v_mul_f32_e32 v173, 0xbfb8aa3b, v165
	v_exp_f32_e32 v173, v173
	v_rcp_f32_e32 v184, v147
	v_add_f32_e32 v147, 1.0, v149
	v_mul_f32_e32 v149, 0xbfb8aa3b, v152
	v_rcp_f32_e32 v185, v147
	v_add_f32_e32 v147, 1.0, v173
	v_exp_f32_e32 v149, v149
	v_mul_f32_e32 v173, 0xbfb8aa3b, v134
	v_exp_f32_e32 v173, v173
	v_rcp_f32_e32 v175, v147
	v_add_f32_e32 v147, 1.0, v149
	v_rcp_f32_e32 v149, v147
	v_add_f32_e32 v147, 1.0, v173
	v_mul_f32_e32 v173, 0xbfb8aa3b, v135
	v_exp_f32_e32 v173, v173
	v_mul_f32_e32 v177, 0xbfb8aa3b, v138
	v_exp_f32_e32 v177, v177
	v_rcp_f32_e32 v186, v147
	v_add_f32_e32 v147, 1.0, v173
	v_mul_f32_e32 v173, 0xbfb8aa3b, v139
	v_rcp_f32_e32 v187, v147
	v_add_f32_e32 v147, 1.0, v177
	v_exp_f32_e32 v173, v173
	v_mul_f32_e32 v177, 0xbfb8aa3b, v136
	v_exp_f32_e32 v177, v177
	v_rcp_f32_e32 v188, v147
	v_add_f32_e32 v147, 1.0, v173
	v_mul_f32_e32 v173, 0xbfb8aa3b, v137
	v_rcp_f32_e32 v189, v147
	v_add_f32_e32 v147, 1.0, v177
	v_exp_f32_e32 v173, v173
	v_mul_f32_e32 v177, 0xbfb8aa3b, v151
	v_exp_f32_e32 v177, v177
	v_rcp_f32_e32 v190, v147
	v_add_f32_e32 v147, 1.0, v173
	v_rcp_f32_e32 v191, v147
	v_add_f32_e32 v147, 1.0, v177
	v_rcp_f32_e32 v173, v147
	v_ashrrev_i32_e32 v147, 31, v146
	v_pk_mul_f32 v[180:181], v[140:141], v[180:181]
	v_lshlrev_b64 v[192:193], 10, v[146:147]
	v_fma_mixlo_f16 v147, v153, v150, 0
	v_cvt_pk_f16_f32 v150, v180, v181
	v_pk_mul_f32 v[182:183], v[144:145], v[182:183]
	v_pack_b32_f16 v180, v147, v150
	v_cvt_pk_f16_f32 v147, v182, v183
	v_pk_mul_f32 v[182:183], v[142:143], v[184:185]
	v_alignbit_b32 v181, v147, v150, 16
	v_cvt_pk_f16_f32 v150, v182, v183
	v_lshrrev_b32_e32 v183, 16, v150
	v_lshl_add_u64 v[132:133], v[132:133], 0, v[192:193]
	v_alignbit_b32 v182, v150, v147, 16
	v_fma_mixhi_f16 v183, v165, v175, 0
	global_store_dwordx4 v[132:133], v[180:183], off offset:-1536 nt
	v_fma_mixlo_f16 v147, v152, v149, 0
	s_nop 0
	v_pk_mul_f32 v[180:181], v[134:135], v[186:187]
	v_pk_mul_f32 v[182:183], v[138:139], v[188:189]
	v_cvt_pk_f16_f32 v149, v180, v181
	v_pack_b32_f16 v180, v147, v149
	v_cvt_pk_f16_f32 v147, v182, v183
	v_pk_mul_f32 v[182:183], v[136:137], v[190:191]
	v_alignbit_b32 v181, v147, v149, 16
	v_cvt_pk_f16_f32 v149, v182, v183
	v_lshrrev_b32_e32 v183, 16, v149
	v_alignbit_b32 v182, v149, v147, 16
	v_fma_mixhi_f16 v183, v151, v173, 0
	global_store_dwordx4 v[132:133], v[180:183], off offset:-1472 nt

;     __device__ __forceinline__ void operator()(const f32x4 (&acc)[2][2][4][2], const pg8::Unit& u, int ui, LAS unsigned char* lds, int wr, int wc, int fr_, int fq_) const {
;     ...
;                     if (pn == 2) {
;                         f16* p = V + (size_t)row * 128 + (wc - 2) * 64 + 8 * fq; *(u32x4*)p = pack8(v[0]); *(u32x4*)(p + 32) = pack8(v[1]);
.LBB0_311:
	s_andn2_b64 vcc, exec, s[10:11]
	s_cbranch_vccnz .LBB0_313
	v_ashrrev_i32_e32 v147, 31, v146
	v_lshlrev_b64 v[132:133], 8, v[146:147]
	v_lshl_add_u64 v[132:133], s[80:81], 0, v[132:133]
	v_cvt_f16_f32_e32 v149, v153
	v_lshl_add_u64 v[146:147], v[130:131], 1, v[132:133]
	v_cvt_f16_f32_e32 v133, v165
	s_mov_b64 s[10:11], 0x9bfff00
	v_lshl_add_u64 v[180:181], v[146:147], 0, s[10:11]
	v_cvt_pk_f16_f32 v131, v140, v141
	v_cvt_pk_f16_f32 v132, v144, v145
	v_cvt_pk_f16_f32 v140, v142, v143
	s_mov_b32 s10, 0x9bff000
	v_pack_b32_f16 v130, v149, v131
	v_alignbit_b32 v131, v132, v131, 16
	v_alignbit_b32 v132, v140, v132, 16
	v_alignbit_b32 v133, v133, v140, 16
	v_add_co_u32_e32 v140, vcc, s10, v146
	v_cvt_f16_f32_e32 v142, v152
	s_nop 0
	v_addc_co_u32_e32 v141, vcc, 0, v147, vcc
	global_store_dwordx4 v[140:141], v[130:133], off offset:3840 nt
	s_nop 1
	v_cvt_f16_f32_e32 v133, v151
	v_cvt_pk_f16_f32 v131, v134, v135
	v_cvt_pk_f16_f32 v132, v138, v139
	v_cvt_pk_f16_f32 v134, v136, v137
	v_pack_b32_f16 v130, v142, v131
	v_alignbit_b32 v131, v132, v131, 16
	v_alignbit_b32 v132, v134, v132, 16
	v_alignbit_b32 v133, v133, v134, 16
	global_store_dwordx4 v[180:181], v[130:133], off offset:64 nt

; #define LAS __attribute__((address_space(3)))
;     __device__ __forceinline__ void operator()(const f32x4 (&acc)[2][2][4][2], const pg8::Unit& u, int ui, LAS unsigned char* lds, int wr, int wc, int fr_, int fq_) const {
;     ...
;         const float* ropeC = (const float*)(ws + WS_ROPE); const float* ropeS = ropeC + 4096 * 32; const float* rot = (const float*)(ws + WS_ROT);
;         f16* Q = (f16*)(ws + WS_Q); f16* K = (f16*)(ws + WS_K); f16* V = (f16*)(ws + WS_V); f16* GA = (f16*)(ws + WS_GA); f16* GF = (f16*)(ws + WS_GF); f16* Z = (f16*)(ws + WS_Z);
;         const int pn = u.pn;
;         const bool is_qk = (pn <= 1) || (pn == 2 && wc < 2);
;         const int row0 = u.pm * 256 + wr * 64 + fr;
;         float rsv[8];
; #pragma unroll
;         for (int i = 0; i < 8; ++i) rsv[i] = (float)((const LAS f16*)(lds + LDS_RS))[ui * 256 + wr * 64 + fr + (i >> 2) * 128 + (i & 3) * 16];
;         if (is_qk) {
;             const float* gain = (pn <= 1) ? qg : kg;
;             const float oscale = (pn <= 1) ? (0.125f * LOG2E) : 1.0f;
;             f32x4 gv[2][2];
; #pragma unroll
;             for (int bj = 0; bj < 2; ++bj)
; #pragma unroll
;                 for (int n = 0; n < 2; ++n) gv[bj][n] = *(const f32x4*)(gain + 32 * bj + 8 * fq + 4 * n) * oscale;
;             const int pos0 = row0 & (SEQ - 1);
;             f32x4 cs[2], sn[2], c16[2], s16[2];
; #pragma unroll
;             for (int n = 0; n < 2; ++n) {
;                 cs[n] = *(const f32x4*)(ropeC + pos0 * 32 + 8 * fq + 4 * n); sn[n] = *(const f32x4*)(ropeS + pos0 * 32 + 8 * fq + 4 * n);
;                 c16[n] = *(const f32x4*)(rot + 8 * fq + 4 * n); s16[n] = *(const f32x4*)(rot + 32 + 8 * fq + 4 * n);
;             }
; #pragma unroll
;             for (int ai = 0; ai < 2; ++ai) {
;                 if (ai == 1) {
; #pragma unroll
;                     for (int k = 0; k < 5; ++k)
; #pragma unroll
;                         for (int n = 0; n < 2; ++n) { const f32x4 c2 = cs[n] * c16[n] - sn[n] * s16[n]; sn[n] = sn[n] * c16[n] + cs[n] * s16[n]; cs[n] = c2; }
;                 }
; #pragma unroll
;                 for (int m = 0; m < 4; ++m) {
;                     const int row = row0 + ai * 128 + m * 16;
;                     const float rs = rsv[ai * 4 + m];
;                     float ss = 0.f;
; #pragma unroll
;                     for (int bj = 0; bj < 2; ++bj)
; #pragma unroll
.LBB0_314:
	s_and_b64 s[10:11], s[0:1], exec
	v_readlane_b32 s10, v254, 51
	v_readlane_b32 s11, v254, 52
	s_cselect_b32 s67, s25, s27
	s_cselect_b32 s71, s24, s26
	s_lshl_b64 s[10:11], s[10:11], 2
	v_lshlrev_b32_e32 v184, 3, v148
	s_add_u32 s10, s71, s10
	v_ashrrev_i32_e32 v185, 31, v184
	s_addc_u32 s11, s67, s11
	v_lshlrev_b64 v[130:131], 2, v[184:185]
	v_lshl_add_u64 v[132:133], s[10:11], 0, v[130:131]
	v_lshlrev_b32_e32 v134, 7, v164
	v_readlane_b32 s10, v254, 10
	v_and_b32_e32 v194, 0x7ff80, v134
	v_readlane_b32 s11, v254, 11
	v_mul_f32_e32 v173, v127, v127
	v_fmac_f32_e32 v173, v126, v126
	v_lshl_add_u64 v[134:135], s[10:11], 0, v[194:195]
	v_readlane_b32 s10, v254, 12
	v_lshl_add_u64 v[134:135], v[134:135], 0, v[130:131]
	v_readlane_b32 s11, v254, 13
	global_load_dwordx4 v[202:205], v[134:135], off
	global_load_dwordx4 v[180:183], v[132:133], off
	global_load_dwordx4 v[206:209], v[132:133], off offset:16
	global_load_dwordx4 v[210:213], v[132:133], off offset:128
	global_load_dwordx4 v[214:217], v[132:133], off offset:144
	v_lshl_add_u64 v[132:133], s[10:11], 0, v[194:195]
	v_lshl_add_u64 v[132:133], v[132:133], 0, v[130:131]
	global_load_dwordx4 v[218:221], v[132:133], off
	global_load_dwordx4 v[150:153], v[134:135], off offset:16
	global_load_dwordx4 v[146:149], v[132:133], off offset:16
	v_readlane_b32 s10, v254, 8
	v_readlane_b32 s11, v254, 9
	v_mov_b32_e32 v132, 0x3e38aa3b
	v_cndmask_b32_e64 v194, 1.0, v132, s[0:1]
	v_lshl_add_u64 v[134:135], s[10:11], 0, v[130:131]
	v_readlane_b32 s10, v254, 14
	v_readlane_b32 s11, v254, 15
	v_fmac_f32_e32 v173, v128, v128
	v_fmac_f32_e32 v173, v129, v129
	v_lshl_add_u64 v[142:143], s[10:11], 0, v[130:131]
	global_load_dwordx4 v[130:133], v[134:135], off offset:16
	global_load_dwordx4 v[138:141], v[134:135], off
	s_nop 0
	global_load_dwordx4 v[134:137], v[142:143], off offset:16
	s_nop 0
	global_load_dwordx4 v[142:145], v[142:143], off
	v_fmac_f32_e32 v173, v122, v122
	v_fmac_f32_e32 v173, v123, v123
	v_fmac_f32_e32 v173, v124, v124
	v_fmac_f32_e32 v173, v125, v125
	v_fmac_f32_e32 v173, v94, v94
	s_lshl_b32 s10, s13, 8
	v_fmac_f32_e32 v173, v95, v95
	s_or_b32 s10, s10, s85
	v_fmac_f32_e32 v173, v96, v96
	s_ashr_i32 s11, s10, 31
	v_fmac_f32_e32 v173, v97, v97
	s_lshl_b64 s[10:11], s[10:11], 1
	v_fmac_f32_e32 v173, v90, v90
	s_add_u32 s10, s44, s10
	v_fmac_f32_e32 v173, v91, v91
	s_addc_u32 s11, s45, s11
	v_fmac_f32_e32 v173, v92, v92
	s_and_b64 s[0:1], s[0:1], exec
	v_fmac_f32_e32 v173, v93, v93
	v_ashrrev_i32_e32 v165, 31, v164
	s_cselect_b32 s0, 10, 8
	v_mov_b32_e32 v177, v173
	s_nop 1
	v_permlane16_swap_b32_e32 v173, v177
	v_lshlrev_b64 v[188:189], s0, v[164:165]
	v_mul_f32_e32 v165, v119, v119
	v_add_f32_e32 v173, v173, v177
	v_fmac_f32_e32 v165, v118, v118
	v_mov_b32_e32 v177, v173
	v_fmac_f32_e32 v165, v120, v120
	s_nop 0
	v_permlane32_swap_b32_e32 v173, v177
	v_fmac_f32_e32 v165, v121, v121
	v_mul_f32_e32 v175, v178, v178
	v_add_f32_e32 v173, v173, v177
	v_fmac_f32_e32 v165, v114, v114
	v_mul_f32_e32 v173, v175, v173
	v_fmac_f32_e32 v165, v115, v115
	v_fmamk_f32 v173, v173, 0x3c800000, v1
	v_fmac_f32_e32 v165, v116, v116
	v_rsq_f32_e32 v173, v173
	v_fmac_f32_e32 v165, v117, v117
	v_fmac_f32_e32 v165, v86, v86
	s_cselect_b32 s1, s11, s12
	s_cselect_b32 s10, s10, s15
	v_fmac_f32_e32 v165, v87, v87
	v_mov_b32_e32 v186, s10
	v_mov_b32_e32 v187, s1
	v_fmac_f32_e32 v165, v88, v88
	v_lshl_add_u64 v[190:191], v[184:185], 1, v[186:187]
	v_mul_f32_e32 v232, v173, v178
	v_fmac_f32_e32 v165, v89, v89
	v_lshl_add_u64 v[230:231], v[190:191], 0, v[188:189]
	v_fmac_f32_e32 v165, v82, v82
	v_fmac_f32_e32 v165, v83, v83
	v_fmac_f32_e32 v165, v84, v84
	v_mov_b64_e32 v[198:199], v[250:251]
	v_fmac_f32_e32 v165, v85, v85
	v_mov_b32_e32 v173, v165
	s_nop 1
	v_permlane16_swap_b32_e32 v165, v173
	s_waitcnt vmcnt(0)
	v_pk_mul_f32 v[234:235], v[202:203], v[232:233] op_sel_hi:[1,0]
	v_pk_mul_f32 v[186:187], v[194:195], v[182:183] op_sel_hi:[0,1]
	v_pk_mul_f32 v[188:189], v[194:195], v[180:181] op_sel_hi:[0,1]
	v_pk_mul_f32 v[192:193], v[194:195], v[212:213] op_sel_hi:[0,1]
	v_pk_mul_f32 v[200:201], v[194:195], v[210:211] op_sel_hi:[0,1]
	v_pk_mul_f32 v[184:185], v[194:195], v[214:215] op_sel_hi:[0,1]
	v_pk_mul_f32 v[210:211], v[96:97], v[192:193]
	v_pk_mul_f32 v[212:213], v[94:95], v[200:201]
	v_pk_mul_f32 v[214:215], v[218:219], v[232:233] op_sel_hi:[1,0]
	v_pk_mul_f32 v[240:241], v[220:221], v[232:233] op_sel_hi:[1,0]
	v_pk_mul_f32 v[178:179], v[194:195], v[208:209] op_sel_hi:[0,1]
	v_pk_mul_f32 v[180:181], v[194:195], v[206:207] op_sel_hi:[0,1]
	v_pk_mul_f32 v[182:183], v[194:195], v[216:217] op_sel_hi:[0,1]
	v_pk_mul_f32 v[216:217], v[128:129], v[186:187]
	v_pk_mul_f32 v[236:237], v[126:127], v[188:189]
	v_pk_mul_f32 v[206:207], v[212:213], v[214:215]
	v_pk_mul_f32 v[238:239], v[204:205], v[232:233] op_sel_hi:[1,0]
	v_pk_mul_f32 v[208:209], v[210:211], v[240:241]
	v_pk_fma_f32 v[206:207], v[236:237], v[234:235], v[206:207] neg_lo:[0,0,1] neg_hi:[0,0,1]
	v_pk_fma_f32 v[208:209], v[216:217], v[238:239], v[208:209] neg_lo:[0,0,1] neg_hi:[0,0,1]
	v_pk_mul_f32 v[242:243], v[150:151], v[232:233] op_sel_hi:[1,0]
	v_pk_mul_f32 v[244:245], v[92:93], v[182:183]
	v_pk_mul_f32 v[246:247], v[90:91], v[184:185]
	v_pk_mul_f32 v[248:249], v[146:147], v[232:233] op_sel_hi:[1,0]
	v_pk_mul_f32 v[226:227], v[152:153], v[232:233] op_sel_hi:[1,0]
	v_pk_mul_f32 v[232:233], v[148:149], v[232:233] op_sel_hi:[1,0]
	v_cvt_pk_f16_f32 v206, v206, v207
	v_cvt_pk_f16_f32 v207, v208, v209
	v_pk_mul_f32 v[250:251], v[124:125], v[178:179]
	v_pk_mul_f32 v[252:253], v[122:123], v[180:181]
	v_pk_mul_f32 v[208:209], v[246:247], v[248:249]
;     __device__ __forceinline__ void operator()(const f32x4 (&acc)[2][2][4][2], const pg8::Unit& u, int ui, LAS unsigned char* lds, int wr, int wc, int fr_, int fq_) const {
;     ...
;                 for (int m = 0; m < 4; ++m) {
;                     const int row = row0 + ai * 128 + m * 16;
;                     const float rs = rsv[ai * 4 + m];
;                     float ss = 0.f;
; #pragma unroll
;                     for (int bj = 0; bj < 2; ++bj)
; #pragma unroll
;                         for (int e = 0; e < 8; ++e) { const float t = acc[ai][bj][m][e >> 2][e & 3]; ss += t * t; }
;                     ss = sum_fq(ss);
;                     const float rn = rs * __builtin_amdgcn_rsqf(ss * (rs * rs) * (1.0f / 64.0f) + EPS);
;                     float o0[8], o1[8];
; #pragma unroll
;                     for (int e = 0; e < 8; ++e) {
;                         const float cc = cs[e >> 2][e & 3] * rn, sv = sn[e >> 2][e & 3] * rn;
;                         const float q0 = acc[ai][0][m][e >> 2][e & 3] * gv[0][e >> 2][e & 3], q1 = acc[ai][1][m][e >> 2][e & 3] * gv[1][e >> 2][e & 3];
;                         o0[e] = q0 * cc - q1 * sv; o1[e] = q1 * cc + q0 * sv;
;                     }
;                     f16* p = (pn <= 1) ? Q + (size_t)row * 512 + (pn * 4 + wc) * 64 + 8 * fq : K + (size_t)row * 128 + wc * 64 + 8 * fq;
;                     *(u32x4*)p = pack8(o0); *(u32x4*)(p + 32) = pack8(o1);
;                     if (m < 3) {
; #pragma unroll
;                         for (int n = 0; n < 2; ++n) { const f32x4 c2 = cs[n] * c16[n] - sn[n] * s16[n]; sn[n] = sn[n] * c16[n] + cs[n] * s16[n]; cs[n] = c2; }
;                     }
	v_pk_mul_f32 v[196:197], v[244:245], v[232:233]
	v_pk_fma_f32 v[208:209], v[252:253], v[242:243], v[208:209] neg_lo:[0,0,1] neg_hi:[0,0,1]
	v_pk_fma_f32 v[196:197], v[250:251], v[226:227], v[196:197] neg_lo:[0,0,1] neg_hi:[0,0,1]
	v_cvt_pk_f16_f32 v208, v208, v209
	v_cvt_pk_f16_f32 v209, v196, v197
	v_pk_mul_f32 v[196:197], v[212:213], v[234:235]
	v_add_f32_e32 v165, v165, v173
	v_pk_fma_f32 v[196:197], v[236:237], v[214:215], v[196:197]
	global_store_dwordx4 v[230:231], v[206:209], off nt
	v_mov_b32_e32 v173, v165
	s_nop 1
	v_permlane32_swap_b32_e32 v165, v173
	v_cvt_pk_f16_f32 v206, v196, v197
	v_pk_mul_f32 v[196:197], v[210:211], v[238:239]
	v_add_f32_e32 v165, v165, v173
	v_pk_fma_f32 v[196:197], v[216:217], v[240:241], v[196:197]
	v_mul_f32_e32 v173, v176, v176
	v_cvt_pk_f16_f32 v207, v196, v197
	v_pk_mul_f32 v[196:197], v[246:247], v[242:243]
	v_mul_f32_e32 v165, v173, v165
	v_pk_fma_f32 v[196:197], v[252:253], v[248:249], v[196:197]
	v_fmamk_f32 v165, v165, 0x3c800000, v1
	v_cvt_pk_f16_f32 v208, v196, v197
	v_pk_mul_f32 v[196:197], v[244:245], v[226:227]
	v_rsq_f32_e32 v165, v165
	v_pk_fma_f32 v[196:197], v[250:251], v[232:233], v[196:197]
	v_pk_mul_f32 v[210:211], v[146:147], v[134:135]
	v_cvt_pk_f16_f32 v209, v196, v197
	global_store_dwordx4 v[230:231], v[206:209], off offset:64 nt
	v_pk_mul_f32 v[196:197], v[220:221], v[144:145]
	v_pk_fma_f32 v[210:211], v[150:151], v[130:131], v[210:211] neg_lo:[0,0,1] neg_hi:[0,0,1]
	v_pk_mul_f32 v[206:207], v[218:219], v[142:143]
	v_pk_mul_f32 v[150:151], v[150:151], v[134:135]
	v_pk_fma_f32 v[196:197], v[204:205], v[140:141], v[196:197] neg_lo:[0,0,1] neg_hi:[0,0,1]
	v_pk_fma_f32 v[206:207], v[202:203], v[138:139], v[206:207] neg_lo:[0,0,1] neg_hi:[0,0,1]
	v_pk_mul_f32 v[204:205], v[204:205], v[144:145]
	v_pk_mul_f32 v[202:203], v[202:203], v[142:143]
	v_pk_fma_f32 v[150:151], v[146:147], v[130:131], v[150:151]
	v_add_u32_e32 v146, 16, v164
	v_pk_fma_f32 v[204:205], v[220:221], v[140:141], v[204:205]
	v_pk_fma_f32 v[202:203], v[218:219], v[138:139], v[202:203]
	v_pk_mul_f32 v[208:209], v[148:149], v[136:137]
	v_mul_f32_e32 v176, v165, v176
	v_ashrrev_i32_e32 v147, 31, v146
	v_pk_fma_f32 v[208:209], v[152:153], v[132:133], v[208:209] neg_lo:[0,0,1] neg_hi:[0,0,1]
	v_pk_mul_f32 v[152:153], v[152:153], v[136:137]
	v_lshlrev_b64 v[146:147], s0, v[146:147]
	v_pk_mul_f32 v[216:217], v[88:89], v[192:193]
	v_pk_mul_f32 v[218:219], v[86:87], v[200:201]
	v_pk_mul_f32 v[220:221], v[202:203], v[176:177] op_sel_hi:[1,0]
	v_pk_mul_f32 v[234:235], v[204:205], v[176:177] op_sel_hi:[1,0]
	v_pk_fma_f32 v[152:153], v[148:149], v[132:133], v[152:153]
	v_lshl_add_u64 v[212:213], v[190:191], 0, v[146:147]
	v_pk_mul_f32 v[214:215], v[206:207], v[176:177] op_sel_hi:[1,0]
	v_pk_mul_f32 v[226:227], v[120:121], v[186:187]
	v_pk_mul_f32 v[230:231], v[118:119], v[188:189]
	v_pk_mul_f32 v[146:147], v[218:219], v[220:221]
	v_pk_mul_f32 v[232:233], v[196:197], v[176:177] op_sel_hi:[1,0]
	v_pk_mul_f32 v[148:149], v[216:217], v[234:235]
	v_pk_fma_f32 v[146:147], v[230:231], v[214:215], v[146:147] neg_lo:[0,0,1] neg_hi:[0,0,1]
	v_pk_fma_f32 v[148:149], v[226:227], v[232:233], v[148:149] neg_lo:[0,0,1] neg_hi:[0,0,1]
	v_pk_mul_f32 v[236:237], v[210:211], v[176:177] op_sel_hi:[1,0]
	v_pk_mul_f32 v[238:239], v[84:85], v[182:183]
	v_pk_mul_f32 v[240:241], v[82:83], v[184:185]
	v_pk_mul_f32 v[242:243], v[150:151], v[176:177] op_sel_hi:[1,0]
	v_pk_mul_f32 v[248:249], v[208:209], v[176:177] op_sel_hi:[1,0]
	v_pk_mul_f32 v[176:177], v[152:153], v[176:177] op_sel_hi:[1,0]
	v_cvt_pk_f16_f32 v146, v146, v147
	v_cvt_pk_f16_f32 v147, v148, v149
	v_pk_mul_f32 v[244:245], v[116:117], v[178:179]
	v_pk_mul_f32 v[246:247], v[114:115], v[180:181]
	v_pk_mul_f32 v[148:149], v[240:241], v[242:243]
	v_pk_mul_f32 v[250:251], v[238:239], v[176:177]
	v_pk_fma_f32 v[148:149], v[246:247], v[236:237], v[148:149] neg_lo:[0,0,1] neg_hi:[0,0,1]
	v_pk_fma_f32 v[250:251], v[244:245], v[248:249], v[250:251] neg_lo:[0,0,1] neg_hi:[0,0,1]
	v_cvt_pk_f16_f32 v148, v148, v149
	v_cvt_pk_f16_f32 v149, v250, v251
	global_store_dwordx4 v[212:213], v[146:149], off nt
	v_mov_b64_e32 v[250:251], v[198:199]
	s_nop 0
	v_pk_mul_f32 v[146:147], v[218:219], v[214:215]
	v_pk_mul_f32 v[148:149], v[216:217], v[232:233]
	v_pk_fma_f32 v[146:147], v[230:231], v[220:221], v[146:147]
	v_pk_fma_f32 v[148:149], v[226:227], v[234:235], v[148:149]
	v_cvt_pk_f16_f32 v146, v146, v147
	v_cvt_pk_f16_f32 v147, v148, v149
	v_pk_mul_f32 v[148:149], v[240:241], v[236:237]
	v_pk_mul_f32 v[214:215], v[238:239], v[248:249]
	v_pk_fma_f32 v[148:149], v[246:247], v[242:243], v[148:149]
	v_pk_fma_f32 v[176:177], v[244:245], v[176:177], v[214:215]
	v_cvt_pk_f16_f32 v148, v148, v149
	v_cvt_pk_f16_f32 v149, v176, v177
	global_store_dwordx4 v[212:213], v[146:149], off offset:64 nt
	v_pk_mul_f32 v[214:215], v[80:81], v[192:193]
	v_pk_mul_f32 v[216:217], v[78:79], v[200:201]
	v_pk_mul_f32 v[148:149], v[142:143], v[202:203]
	v_pk_mul_f32 v[146:147], v[144:145], v[204:205]
	v_pk_fma_f32 v[212:213], v[138:139], v[206:207], v[148:149] neg_lo:[0,0,1] neg_hi:[0,0,1]
	v_pk_mul_f32 v[148:149], v[142:143], v[206:207]
	v_pk_fma_f32 v[176:177], v[140:141], v[196:197], v[146:147] neg_lo:[0,0,1] neg_hi:[0,0,1]
	v_pk_fma_f32 v[202:203], v[138:139], v[202:203], v[148:149]
	v_pk_mul_f32 v[148:149], v[134:135], v[150:151]
	v_pk_mul_f32 v[146:147], v[144:145], v[196:197]
	v_pk_fma_f32 v[206:207], v[130:131], v[210:211], v[148:149] neg_lo:[0,0,1] neg_hi:[0,0,1]
	v_mul_f32_e32 v148, v111, v111
	v_fmac_f32_e32 v148, v110, v110
	v_fmac_f32_e32 v148, v112, v112
	v_fmac_f32_e32 v148, v113, v113
	v_fmac_f32_e32 v148, v106, v106
;     __device__ __forceinline__ void operator()(const f32x4 (&acc)[2][2][4][2], const pg8::Unit& u, int ui, LAS unsigned char* lds, int wr, int wc, int fr_, int fq_) const {
;     ...
;                 for (int m = 0; m < 4; ++m) {
;                     const int row = row0 + ai * 128 + m * 16;
;                     const float rs = rsv[ai * 4 + m];
;                     float ss = 0.f;
; #pragma unroll
;                     for (int bj = 0; bj < 2; ++bj)
; #pragma unroll
;                         for (int e = 0; e < 8; ++e) { const float t = acc[ai][bj][m][e >> 2][e & 3]; ss += t * t; }
;                     ss = sum_fq(ss);
;                     const float rn = rs * __builtin_amdgcn_rsqf(ss * (rs * rs) * (1.0f / 64.0f) + EPS);
;                     float o0[8], o1[8];
; #pragma unroll
;                     for (int e = 0; e < 8; ++e) {
;                         const float cc = cs[e >> 2][e & 3] * rn, sv = sn[e >> 2][e & 3] * rn;
;                         const float q0 = acc[ai][0][m][e >> 2][e & 3] * gv[0][e >> 2][e & 3], q1 = acc[ai][1][m][e >> 2][e & 3] * gv[1][e >> 2][e & 3];
;                         o0[e] = q0 * cc - q1 * sv; o1[e] = q1 * cc + q0 * sv;
;                     }
;                     f16* p = (pn <= 1) ? Q + (size_t)row * 512 + (pn * 4 + wc) * 64 + 8 * fq : K + (size_t)row * 128 + wc * 64 + 8 * fq;
;                     *(u32x4*)p = pack8(o0); *(u32x4*)(p + 32) = pack8(o1);
;                     if (m < 3) {
; #pragma unroll
;                         for (int n = 0; n < 2; ++n) { const f32x4 c2 = cs[n] * c16[n] - sn[n] * s16[n]; sn[n] = sn[n] * c16[n] + cs[n] * s16[n]; cs[n] = c2; }
;                     }
	v_fmac_f32_e32 v148, v107, v107
	v_fmac_f32_e32 v148, v108, v108
	v_fmac_f32_e32 v148, v109, v109
	v_fmac_f32_e32 v148, v78, v78
	v_fmac_f32_e32 v148, v79, v79
	v_fmac_f32_e32 v148, v80, v80
	v_fmac_f32_e32 v148, v81, v81
	v_fmac_f32_e32 v148, v74, v74
	v_fmac_f32_e32 v148, v75, v75
	v_fmac_f32_e32 v148, v76, v76
	v_fmac_f32_e32 v148, v77, v77
	v_mov_b32_e32 v149, v148
	s_nop 1
	v_permlane16_swap_b32_e32 v148, v149
	v_add_f32_e32 v148, v148, v149
	v_mov_b32_e32 v149, v148
	s_nop 1
	v_permlane32_swap_b32_e32 v148, v149
	v_add_f32_e32 v148, v148, v149
	v_mul_f32_e32 v149, v174, v174
	v_mul_f32_e32 v148, v149, v148
	v_fmamk_f32 v148, v148, 0x3c800000, v1
	v_rsq_f32_e32 v165, v148
	v_pk_fma_f32 v[196:197], v[140:141], v[204:205], v[146:147]
	v_pk_mul_f32 v[146:147], v[136:137], v[152:153]
	v_pk_mul_f32 v[148:149], v[134:135], v[210:211]
	v_pk_fma_f32 v[204:205], v[132:133], v[208:209], v[146:147] neg_lo:[0,0,1] neg_hi:[0,0,1]
	v_pk_mul_f32 v[146:147], v[136:137], v[208:209]
	v_mul_f32_e32 v174, v165, v174
	v_pk_fma_f32 v[152:153], v[132:133], v[152:153], v[146:147]
	v_add_u32_e32 v146, 32, v164
	v_ashrrev_i32_e32 v147, 31, v146
	v_lshlrev_b64 v[146:147], s0, v[146:147]
	v_pk_mul_f32 v[218:219], v[202:203], v[174:175] op_sel_hi:[1,0]
	v_pk_mul_f32 v[232:233], v[196:197], v[174:175] op_sel_hi:[1,0]
	v_pk_fma_f32 v[150:151], v[130:131], v[150:151], v[148:149]
	v_lshl_add_u64 v[208:209], v[190:191], 0, v[146:147]
	v_pk_mul_f32 v[210:211], v[212:213], v[174:175] op_sel_hi:[1,0]
	v_pk_mul_f32 v[220:221], v[112:113], v[186:187]
	v_pk_mul_f32 v[226:227], v[110:111], v[188:189]
	v_pk_mul_f32 v[146:147], v[216:217], v[218:219]
	v_pk_mul_f32 v[230:231], v[176:177], v[174:175] op_sel_hi:[1,0]
	v_pk_mul_f32 v[148:149], v[214:215], v[232:233]
	v_pk_fma_f32 v[146:147], v[226:227], v[210:211], v[146:147] neg_lo:[0,0,1] neg_hi:[0,0,1]
	v_pk_fma_f32 v[148:149], v[220:221], v[230:231], v[148:149] neg_lo:[0,0,1] neg_hi:[0,0,1]
	v_pk_mul_f32 v[234:235], v[206:207], v[174:175] op_sel_hi:[1,0]
	v_pk_mul_f32 v[236:237], v[76:77], v[182:183]
	v_pk_mul_f32 v[238:239], v[74:75], v[184:185]
	v_pk_mul_f32 v[240:241], v[150:151], v[174:175] op_sel_hi:[1,0]
	v_pk_mul_f32 v[246:247], v[204:205], v[174:175] op_sel_hi:[1,0]
	v_pk_mul_f32 v[174:175], v[152:153], v[174:175] op_sel_hi:[1,0]
	v_cvt_pk_f16_f32 v146, v146, v147
	v_cvt_pk_f16_f32 v147, v148, v149
	v_pk_mul_f32 v[242:243], v[108:109], v[178:179]
	v_pk_mul_f32 v[244:245], v[106:107], v[180:181]
	v_pk_mul_f32 v[148:149], v[238:239], v[240:241]
	v_pk_mul_f32 v[248:249], v[236:237], v[174:175]
	v_pk_fma_f32 v[148:149], v[244:245], v[234:235], v[148:149] neg_lo:[0,0,1] neg_hi:[0,0,1]
	v_pk_fma_f32 v[248:249], v[242:243], v[246:247], v[248:249] neg_lo:[0,0,1] neg_hi:[0,0,1]
	v_cvt_pk_f16_f32 v148, v148, v149
	v_cvt_pk_f16_f32 v149, v248, v249
	global_store_dwordx4 v[208:209], v[146:149], off nt
	s_nop 1
	v_pk_mul_f32 v[146:147], v[216:217], v[210:211]
	v_pk_mul_f32 v[148:149], v[214:215], v[230:231]
	v_pk_fma_f32 v[146:147], v[226:227], v[218:219], v[146:147]
	v_pk_fma_f32 v[148:149], v[220:221], v[232:233], v[148:149]
	v_cvt_pk_f16_f32 v146, v146, v147
	v_cvt_pk_f16_f32 v147, v148, v149
	v_pk_mul_f32 v[148:149], v[238:239], v[234:235]
	v_pk_mul_f32 v[210:211], v[236:237], v[246:247]
	v_pk_fma_f32 v[148:149], v[244:245], v[240:241], v[148:149]
	v_pk_fma_f32 v[174:175], v[242:243], v[174:175], v[210:211]
	v_cvt_pk_f16_f32 v148, v148, v149
	v_cvt_pk_f16_f32 v149, v174, v175
	global_store_dwordx4 v[208:209], v[146:149], off offset:64 nt
	v_pk_mul_f32 v[214:215], v[70:71], v[200:201]
	v_pk_mul_f32 v[218:219], v[104:105], v[186:187]
	v_pk_mul_f32 v[146:147], v[144:145], v[196:197]
	v_pk_mul_f32 v[148:149], v[142:143], v[202:203]
	v_pk_fma_f32 v[174:175], v[140:141], v[176:177], v[146:147] neg_lo:[0,0,1] neg_hi:[0,0,1]
	v_pk_fma_f32 v[208:209], v[138:139], v[212:213], v[148:149] neg_lo:[0,0,1] neg_hi:[0,0,1]
	v_pk_mul_f32 v[146:147], v[144:145], v[176:177]
	v_pk_mul_f32 v[148:149], v[142:143], v[212:213]
	v_pk_fma_f32 v[176:177], v[140:141], v[196:197], v[146:147]
	v_pk_fma_f32 v[196:197], v[138:139], v[202:203], v[148:149]
	v_pk_mul_f32 v[148:149], v[134:135], v[150:151]
	v_pk_mul_f32 v[146:147], v[136:137], v[152:153]
	v_pk_fma_f32 v[210:211], v[130:131], v[206:207], v[148:149] neg_lo:[0,0,1] neg_hi:[0,0,1]
	v_mul_f32_e32 v148, v103, v103
	v_fmac_f32_e32 v148, v102, v102
	v_fmac_f32_e32 v148, v104, v104
	v_fmac_f32_e32 v148, v105, v105
	v_fmac_f32_e32 v148, v98, v98
	v_fmac_f32_e32 v148, v99, v99
	v_fmac_f32_e32 v148, v100, v100
	v_fmac_f32_e32 v148, v101, v101
	v_fmac_f32_e32 v148, v70, v70
	v_fmac_f32_e32 v148, v71, v71
	v_fmac_f32_e32 v148, v72, v72
	v_fmac_f32_e32 v148, v73, v73
	v_fmac_f32_e32 v148, v66, v66
	v_fmac_f32_e32 v148, v67, v67
	v_fmac_f32_e32 v148, v68, v68
	v_fmac_f32_e32 v148, v69, v69
	v_mov_b32_e32 v149, v148
	s_nop 1
	v_permlane16_swap_b32_e32 v148, v149
	v_add_f32_e32 v148, v148, v149
	v_mov_b32_e32 v149, v148
	s_nop 1
	v_permlane32_swap_b32_e32 v148, v149
	v_add_f32_e32 v148, v148, v149
	v_mul_f32_e32 v149, v172, v172
	v_mul_f32_e32 v148, v149, v148
	v_fmamk_f32 v148, v148, 0x3c800000, v1
	v_rsq_f32_e32 v165, v148
	v_pk_fma_f32 v[202:203], v[132:133], v[204:205], v[146:147] neg_lo:[0,0,1] neg_hi:[0,0,1]
	v_pk_mul_f32 v[146:147], v[136:137], v[204:205]
	v_pk_mul_f32 v[148:149], v[134:135], v[206:207]
	v_pk_fma_f32 v[152:153], v[132:133], v[152:153], v[146:147]
	v_add_u32_e32 v146, 48, v164
	v_mul_f32_e32 v172, v165, v172
	v_ashrrev_i32_e32 v147, 31, v146
	v_lshlrev_b64 v[146:147], s0, v[146:147]
	v_pk_mul_f32 v[212:213], v[72:73], v[192:193]
	v_pk_mul_f32 v[216:217], v[196:197], v[172:173] op_sel_hi:[1,0]
;     __device__ __forceinline__ void operator()(const f32x4 (&acc)[2][2][4][2], const pg8::Unit& u, int ui, LAS unsigned char* lds, int wr, int wc, int fr_, int fq_) const {
;     ...
;             for (int ai = 0; ai < 2; ++ai) {
;                 if (ai == 1) {
; #pragma unroll
;                     for (int k = 0; k < 5; ++k)
; #pragma unroll
;                         for (int n = 0; n < 2; ++n) { const f32x4 c2 = cs[n] * c16[n] - sn[n] * s16[n]; sn[n] = sn[n] * c16[n] + cs[n] * s16[n]; cs[n] = c2; }
;                 }
; #pragma unroll
;                 for (int m = 0; m < 4; ++m) {
;                     const int row = row0 + ai * 128 + m * 16;
;                     const float rs = rsv[ai * 4 + m];
;                     float ss = 0.f;
; #pragma unroll
;                     for (int bj = 0; bj < 2; ++bj)
; #pragma unroll
;                         for (int e = 0; e < 8; ++e) { const float t = acc[ai][bj][m][e >> 2][e & 3]; ss += t * t; }
;                     ss = sum_fq(ss);
;                     const float rn = rs * __builtin_amdgcn_rsqf(ss * (rs * rs) * (1.0f / 64.0f) + EPS);
;                     float o0[8], o1[8];
; #pragma unroll
;                     for (int e = 0; e < 8; ++e) {
;                         const float cc = cs[e >> 2][e & 3] * rn, sv = sn[e >> 2][e & 3] * rn;
;                         const float q0 = acc[ai][0][m][e >> 2][e & 3] * gv[0][e >> 2][e & 3], q1 = acc[ai][1][m][e >> 2][e & 3] * gv[1][e >> 2][e & 3];
;                         o0[e] = q0 * cc - q1 * sv; o1[e] = q1 * cc + q0 * sv;
;                     }
;                     f16* p = (pn <= 1) ? Q + (size_t)row * 512 + (pn * 4 + wc) * 64 + 8 * fq : K + (size_t)row * 128 + wc * 64 + 8 * fq;
;                     *(u32x4*)p = pack8(o0); *(u32x4*)(p + 32) = pack8(o1);
;                     if (m < 3) {
; #pragma unroll
;                         for (int n = 0; n < 2; ++n) { const f32x4 c2 = cs[n] * c16[n] - sn[n] * s16[n]; sn[n] = sn[n] * c16[n] + cs[n] * s16[n]; cs[n] = c2; }
;                     }
	v_pk_mul_f32 v[230:231], v[176:177], v[172:173] op_sel_hi:[1,0]
	v_pk_fma_f32 v[150:151], v[130:131], v[150:151], v[148:149]
	v_lshl_add_u64 v[204:205], v[190:191], 0, v[146:147]
	v_pk_mul_f32 v[206:207], v[208:209], v[172:173] op_sel_hi:[1,0]
	v_pk_mul_f32 v[220:221], v[102:103], v[188:189]
	v_pk_mul_f32 v[146:147], v[214:215], v[216:217]
	v_pk_mul_f32 v[226:227], v[174:175], v[172:173] op_sel_hi:[1,0]
	v_pk_mul_f32 v[148:149], v[212:213], v[230:231]
	v_pk_fma_f32 v[146:147], v[220:221], v[206:207], v[146:147] neg_lo:[0,0,1] neg_hi:[0,0,1]
	v_pk_fma_f32 v[148:149], v[218:219], v[226:227], v[148:149] neg_lo:[0,0,1] neg_hi:[0,0,1]
	v_pk_mul_f32 v[232:233], v[210:211], v[172:173] op_sel_hi:[1,0]
	v_pk_mul_f32 v[234:235], v[68:69], v[182:183]
	v_pk_mul_f32 v[236:237], v[66:67], v[184:185]
	v_pk_mul_f32 v[238:239], v[150:151], v[172:173] op_sel_hi:[1,0]
	v_pk_mul_f32 v[244:245], v[202:203], v[172:173] op_sel_hi:[1,0]
	v_pk_mul_f32 v[172:173], v[152:153], v[172:173] op_sel_hi:[1,0]
	v_cvt_pk_f16_f32 v146, v146, v147
	v_cvt_pk_f16_f32 v147, v148, v149
	v_pk_mul_f32 v[240:241], v[100:101], v[178:179]
	v_pk_mul_f32 v[242:243], v[98:99], v[180:181]
	v_pk_mul_f32 v[148:149], v[236:237], v[238:239]
	v_pk_mul_f32 v[246:247], v[234:235], v[172:173]
	v_pk_fma_f32 v[148:149], v[242:243], v[232:233], v[148:149] neg_lo:[0,0,1] neg_hi:[0,0,1]
	v_pk_fma_f32 v[246:247], v[240:241], v[244:245], v[246:247] neg_lo:[0,0,1] neg_hi:[0,0,1]
	v_cvt_pk_f16_f32 v148, v148, v149
	v_cvt_pk_f16_f32 v149, v246, v247
	global_store_dwordx4 v[204:205], v[146:149], off nt
	v_mul_f32_e32 v165, v63, v63
	v_fmac_f32_e32 v165, v62, v62
	v_pk_mul_f32 v[146:147], v[214:215], v[206:207]
	v_pk_mul_f32 v[148:149], v[212:213], v[226:227]
	v_pk_fma_f32 v[146:147], v[220:221], v[216:217], v[146:147]
	v_pk_fma_f32 v[148:149], v[218:219], v[230:231], v[148:149]
	v_cvt_pk_f16_f32 v146, v146, v147
	v_cvt_pk_f16_f32 v147, v148, v149
	v_pk_mul_f32 v[148:149], v[236:237], v[232:233]
	v_pk_mul_f32 v[206:207], v[234:235], v[244:245]
	v_pk_fma_f32 v[148:149], v[242:243], v[238:239], v[148:149]
	v_pk_fma_f32 v[172:173], v[240:241], v[172:173], v[206:207]
	v_cvt_pk_f16_f32 v148, v148, v149
	v_cvt_pk_f16_f32 v149, v172, v173
	v_pk_mul_f32 v[172:173], v[144:145], v[174:175]
	global_store_dwordx4 v[204:205], v[146:149], off offset:64 nt
	v_pk_fma_f32 v[172:173], v[140:141], v[176:177], v[172:173]
	v_fmac_f32_e32 v165, v64, v64
	v_pk_mul_f32 v[146:147], v[144:145], v[176:177]
	v_pk_mul_f32 v[176:177], v[136:137], v[152:153]
	v_pk_fma_f32 v[146:147], v[140:141], v[174:175], v[146:147] neg_lo:[0,0,1] neg_hi:[0,0,1]
	v_pk_fma_f32 v[176:177], v[132:133], v[202:203], v[176:177] neg_lo:[0,0,1] neg_hi:[0,0,1]
	v_pk_mul_f32 v[202:203], v[136:137], v[202:203]
	v_fmac_f32_e32 v165, v65, v65
	v_pk_fma_f32 v[152:153], v[132:133], v[152:153], v[202:203]
	v_pk_mul_f32 v[202:203], v[144:145], v[172:173]
	v_fmac_f32_e32 v165, v58, v58
	v_pk_fma_f32 v[202:203], v[140:141], v[146:147], v[202:203] neg_lo:[0,0,1] neg_hi:[0,0,1]
	v_pk_mul_f32 v[146:147], v[144:145], v[146:147]
	v_fmac_f32_e32 v165, v59, v59
	v_pk_fma_f32 v[146:147], v[140:141], v[172:173], v[146:147]
	v_pk_mul_f32 v[172:173], v[136:137], v[152:153]
	v_fmac_f32_e32 v165, v60, v60
	v_pk_fma_f32 v[172:173], v[132:133], v[176:177], v[172:173] neg_lo:[0,0,1] neg_hi:[0,0,1]
	v_pk_mul_f32 v[176:177], v[136:137], v[176:177]
	v_fmac_f32_e32 v165, v61, v61
	v_pk_fma_f32 v[152:153], v[132:133], v[152:153], v[176:177]
	v_pk_mul_f32 v[176:177], v[144:145], v[146:147]
	v_fmac_f32_e32 v165, v30, v30
	v_pk_fma_f32 v[176:177], v[140:141], v[202:203], v[176:177] neg_lo:[0,0,1] neg_hi:[0,0,1]
	v_pk_mul_f32 v[202:203], v[144:145], v[202:203]
	v_fmac_f32_e32 v165, v31, v31
	v_pk_fma_f32 v[146:147], v[140:141], v[146:147], v[202:203]
	v_pk_mul_f32 v[202:203], v[136:137], v[152:153]
	v_fmac_f32_e32 v165, v32, v32
	v_pk_fma_f32 v[202:203], v[132:133], v[172:173], v[202:203] neg_lo:[0,0,1] neg_hi:[0,0,1]
	v_pk_mul_f32 v[172:173], v[136:137], v[172:173]
	v_fmac_f32_e32 v165, v33, v33
	v_pk_fma_f32 v[152:153], v[132:133], v[152:153], v[172:173]
	v_pk_mul_f32 v[172:173], v[144:145], v[146:147]
	v_pk_mul_f32 v[174:175], v[142:143], v[208:209]
	v_pk_fma_f32 v[172:173], v[140:141], v[176:177], v[172:173] neg_lo:[0,0,1] neg_hi:[0,0,1]
	v_pk_mul_f32 v[176:177], v[144:145], v[176:177]
	v_fmac_f32_e32 v165, v26, v26
	v_pk_fma_f32 v[146:147], v[140:141], v[146:147], v[176:177]
	v_pk_mul_f32 v[176:177], v[136:137], v[152:153]
	v_pk_mul_f32 v[148:149], v[142:143], v[196:197]
	v_pk_fma_f32 v[176:177], v[132:133], v[202:203], v[176:177] neg_lo:[0,0,1] neg_hi:[0,0,1]
	v_pk_mul_f32 v[202:203], v[136:137], v[202:203]
	v_pk_fma_f32 v[174:175], v[138:139], v[196:197], v[174:175]
	v_pk_mul_f32 v[204:205], v[134:135], v[210:211]
	v_pk_fma_f32 v[152:153], v[132:133], v[152:153], v[202:203]
	v_pk_mul_f32 v[202:203], v[144:145], v[146:147]
	v_fmac_f32_e32 v165, v27, v27
	v_pk_fma_f32 v[148:149], v[138:139], v[208:209], v[148:149] neg_lo:[0,0,1] neg_hi:[0,0,1]
	v_pk_mul_f32 v[196:197], v[134:135], v[150:151]
	v_pk_fma_f32 v[150:151], v[130:131], v[150:151], v[204:205]
	v_pk_mul_f32 v[204:205], v[142:143], v[174:175]
	v_pk_fma_f32 v[202:203], v[140:141], v[172:173], v[202:203] neg_lo:[0,0,1] neg_hi:[0,0,1]
	v_pk_mul_f32 v[172:173], v[144:145], v[172:173]
	v_fmac_f32_e32 v165, v28, v28
	v_pk_fma_f32 v[204:205], v[138:139], v[148:149], v[204:205] neg_lo:[0,0,1] neg_hi:[0,0,1]
	v_pk_mul_f32 v[148:149], v[142:143], v[148:149]
	v_pk_fma_f32 v[172:173], v[140:141], v[146:147], v[172:173]
	v_pk_mul_f32 v[146:147], v[136:137], v[152:153]
	v_fmac_f32_e32 v165, v29, v29
;     __device__ __forceinline__ void operator()(const f32x4 (&acc)[2][2][4][2], const pg8::Unit& u, int ui, LAS unsigned char* lds, int wr, int wc, int fr_, int fq_) const {
;     ...
;                 for (int m = 0; m < 4; ++m) {
;                     const int row = row0 + ai * 128 + m * 16;
;                     const float rs = rsv[ai * 4 + m];
;                     float ss = 0.f;
; #pragma unroll
;                     for (int bj = 0; bj < 2; ++bj)
; #pragma unroll
;                         for (int e = 0; e < 8; ++e) { const float t = acc[ai][bj][m][e >> 2][e & 3]; ss += t * t; }
;                     ss = sum_fq(ss);
;                     const float rn = rs * __builtin_amdgcn_rsqf(ss * (rs * rs) * (1.0f / 64.0f) + EPS);
;                     float o0[8], o1[8];
; #pragma unroll
;                     for (int e = 0; e < 8; ++e) {
;                         const float cc = cs[e >> 2][e & 3] * rn, sv = sn[e >> 2][e & 3] * rn;
;                         const float q0 = acc[ai][0][m][e >> 2][e & 3] * gv[0][e >> 2][e & 3], q1 = acc[ai][1][m][e >> 2][e & 3] * gv[1][e >> 2][e & 3];
;                         o0[e] = q0 * cc - q1 * sv; o1[e] = q1 * cc + q0 * sv;
;                     }
;                     f16* p = (pn <= 1) ? Q + (size_t)row * 512 + (pn * 4 + wc) * 64 + 8 * fq : K + (size_t)row * 128 + wc * 64 + 8 * fq;
;                     *(u32x4*)p = pack8(o0); *(u32x4*)(p + 32) = pack8(o1);
;                     if (m < 3) {
; #pragma unroll
;                         for (int n = 0; n < 2; ++n) { const f32x4 c2 = cs[n] * c16[n] - sn[n] * s16[n]; sn[n] = sn[n] * c16[n] + cs[n] * s16[n]; cs[n] = c2; }
;                     }
	v_pk_fma_f32 v[196:197], v[130:131], v[210:211], v[196:197] neg_lo:[0,0,1] neg_hi:[0,0,1]
	v_pk_fma_f32 v[148:149], v[138:139], v[174:175], v[148:149]
	v_pk_mul_f32 v[174:175], v[134:135], v[150:151]
	v_pk_fma_f32 v[206:207], v[132:133], v[176:177], v[146:147] neg_lo:[0,0,1] neg_hi:[0,0,1]
	v_pk_mul_f32 v[146:147], v[136:137], v[176:177]
	v_mov_b32_e32 v176, v165
	v_pk_fma_f32 v[174:175], v[130:131], v[196:197], v[174:175] neg_lo:[0,0,1] neg_hi:[0,0,1]
	v_pk_mul_f32 v[196:197], v[134:135], v[196:197]
	v_permlane16_swap_b32_e32 v165, v176
	v_pk_fma_f32 v[150:151], v[130:131], v[150:151], v[196:197]
	v_pk_mul_f32 v[196:197], v[142:143], v[148:149]
	v_add_f32_e32 v165, v165, v176
	v_pk_fma_f32 v[196:197], v[138:139], v[204:205], v[196:197] neg_lo:[0,0,1] neg_hi:[0,0,1]
	v_pk_mul_f32 v[204:205], v[142:143], v[204:205]
	v_mov_b32_e32 v176, v165
	v_pk_fma_f32 v[148:149], v[138:139], v[148:149], v[204:205]
	v_pk_mul_f32 v[204:205], v[134:135], v[150:151]
	v_permlane32_swap_b32_e32 v165, v176
	v_pk_fma_f32 v[204:205], v[130:131], v[174:175], v[204:205] neg_lo:[0,0,1] neg_hi:[0,0,1]
	v_pk_mul_f32 v[174:175], v[134:135], v[174:175]
	v_add_f32_e32 v165, v165, v176
	v_mul_f32_e32 v176, v170, v170
	v_pk_fma_f32 v[150:151], v[130:131], v[150:151], v[174:175]
	v_pk_mul_f32 v[174:175], v[142:143], v[148:149]
	v_mul_f32_e32 v165, v176, v165
	v_pk_fma_f32 v[174:175], v[138:139], v[196:197], v[174:175] neg_lo:[0,0,1] neg_hi:[0,0,1]
	v_pk_mul_f32 v[196:197], v[142:143], v[196:197]
	v_fmamk_f32 v165, v165, 0x3c800000, v1
	v_pk_fma_f32 v[148:149], v[138:139], v[148:149], v[196:197]
	v_pk_mul_f32 v[196:197], v[134:135], v[150:151]
	v_rsq_f32_e32 v165, v165
	v_pk_fma_f32 v[196:197], v[130:131], v[204:205], v[196:197] neg_lo:[0,0,1] neg_hi:[0,0,1]
	v_pk_mul_f32 v[204:205], v[134:135], v[204:205]
	v_pk_fma_f32 v[152:153], v[132:133], v[152:153], v[146:147]
	v_pk_fma_f32 v[150:151], v[130:131], v[150:151], v[204:205]
	v_pk_mul_f32 v[204:205], v[142:143], v[148:149]
	v_add_u32_e32 v146, 0x80, v164
	v_pk_fma_f32 v[204:205], v[138:139], v[174:175], v[204:205] neg_lo:[0,0,1] neg_hi:[0,0,1]
	v_pk_mul_f32 v[174:175], v[142:143], v[174:175]
	v_mul_f32_e32 v170, v165, v170
	v_pk_fma_f32 v[174:175], v[138:139], v[148:149], v[174:175]
	v_pk_mul_f32 v[148:149], v[134:135], v[150:151]
	v_ashrrev_i32_e32 v147, 31, v146
	v_pk_fma_f32 v[208:209], v[130:131], v[196:197], v[148:149] neg_lo:[0,0,1] neg_hi:[0,0,1]
	v_pk_mul_f32 v[148:149], v[134:135], v[196:197]
	v_lshlrev_b64 v[146:147], s0, v[146:147]
	v_pk_mul_f32 v[210:211], v[32:33], v[192:193]
	v_pk_mul_f32 v[212:213], v[30:31], v[200:201]
	v_pk_mul_f32 v[214:215], v[174:175], v[170:171] op_sel_hi:[1,0]
	v_pk_mul_f32 v[226:227], v[172:173], v[170:171] op_sel_hi:[1,0]
	v_pk_fma_f32 v[150:151], v[130:131], v[150:151], v[148:149]
	v_lshl_add_u64 v[176:177], v[190:191], 0, v[146:147]
	v_pk_mul_f32 v[196:197], v[204:205], v[170:171] op_sel_hi:[1,0]
	v_pk_mul_f32 v[216:217], v[64:65], v[186:187]
	v_pk_mul_f32 v[218:219], v[62:63], v[188:189]
	v_pk_mul_f32 v[146:147], v[212:213], v[214:215]
	v_pk_mul_f32 v[220:221], v[202:203], v[170:171] op_sel_hi:[1,0]
	v_pk_mul_f32 v[148:149], v[210:211], v[226:227]
	v_pk_fma_f32 v[146:147], v[218:219], v[196:197], v[146:147] neg_lo:[0,0,1] neg_hi:[0,0,1]
	v_pk_fma_f32 v[148:149], v[216:217], v[220:221], v[148:149] neg_lo:[0,0,1] neg_hi:[0,0,1]
	v_pk_mul_f32 v[232:233], v[28:29], v[182:183]
	v_pk_mul_f32 v[234:235], v[26:27], v[184:185]
	v_pk_mul_f32 v[236:237], v[150:151], v[170:171] op_sel_hi:[1,0]
	v_pk_mul_f32 v[244:245], v[152:153], v[170:171] op_sel_hi:[1,0]
	v_cvt_pk_f16_f32 v146, v146, v147
	v_cvt_pk_f16_f32 v147, v148, v149
	v_pk_mul_f32 v[230:231], v[208:209], v[170:171] op_sel_hi:[1,0]
	v_pk_mul_f32 v[238:239], v[60:61], v[178:179]
	v_pk_mul_f32 v[240:241], v[58:59], v[180:181]
	v_pk_mul_f32 v[148:149], v[234:235], v[236:237]
	v_pk_mul_f32 v[242:243], v[206:207], v[170:171] op_sel_hi:[1,0]
	v_pk_mul_f32 v[246:247], v[232:233], v[244:245]
	v_pk_fma_f32 v[148:149], v[240:241], v[230:231], v[148:149] neg_lo:[0,0,1] neg_hi:[0,0,1]
	v_pk_fma_f32 v[246:247], v[238:239], v[242:243], v[246:247] neg_lo:[0,0,1] neg_hi:[0,0,1]
	v_cvt_pk_f16_f32 v148, v148, v149
	v_cvt_pk_f16_f32 v149, v246, v247
	global_store_dwordx4 v[176:177], v[146:149], off nt
	s_nop 1
	v_pk_mul_f32 v[146:147], v[212:213], v[196:197]
	v_pk_mul_f32 v[148:149], v[210:211], v[220:221]
	v_pk_fma_f32 v[146:147], v[218:219], v[214:215], v[146:147]
	v_pk_fma_f32 v[148:149], v[216:217], v[226:227], v[148:149]
	v_cvt_pk_f16_f32 v146, v146, v147
	v_cvt_pk_f16_f32 v147, v148, v149
	v_pk_mul_f32 v[148:149], v[234:235], v[230:231]
	v_pk_mul_f32 v[196:197], v[232:233], v[242:243]
	v_pk_fma_f32 v[148:149], v[240:241], v[236:237], v[148:149]
	v_pk_fma_f32 v[196:197], v[238:239], v[244:245], v[196:197]
	v_cvt_pk_f16_f32 v148, v148, v149
	v_cvt_pk_f16_f32 v149, v196, v197
	global_store_dwordx4 v[176:177], v[146:149], off offset:64 nt
	v_pk_mul_f32 v[210:211], v[24:25], v[192:193]
	v_pk_mul_f32 v[212:213], v[22:23], v[200:201]
	v_pk_mul_f32 v[148:149], v[142:143], v[174:175]
	v_pk_mul_f32 v[146:147], v[144:145], v[172:173]
	v_pk_fma_f32 v[196:197], v[138:139], v[204:205], v[148:149] neg_lo:[0,0,1] neg_hi:[0,0,1]
	v_pk_mul_f32 v[148:149], v[142:143], v[204:205]
	v_pk_fma_f32 v[176:177], v[140:141], v[202:203], v[146:147] neg_lo:[0,0,1] neg_hi:[0,0,1]
	v_pk_fma_f32 v[174:175], v[138:139], v[174:175], v[148:149]
	v_pk_mul_f32 v[148:149], v[134:135], v[150:151]
	v_pk_mul_f32 v[146:147], v[144:145], v[202:203]
	v_pk_fma_f32 v[204:205], v[130:131], v[208:209], v[148:149] neg_lo:[0,0,1] neg_hi:[0,0,1]
	v_mul_f32_e32 v148, v55, v55
	v_fmac_f32_e32 v148, v54, v54
;     __device__ __forceinline__ void operator()(const f32x4 (&acc)[2][2][4][2], const pg8::Unit& u, int ui, LAS unsigned char* lds, int wr, int wc, int fr_, int fq_) const {
;     ...
;                 for (int m = 0; m < 4; ++m) {
;                     const int row = row0 + ai * 128 + m * 16;
;                     const float rs = rsv[ai * 4 + m];
;                     float ss = 0.f;
; #pragma unroll
;                     for (int bj = 0; bj < 2; ++bj)
; #pragma unroll
;                         for (int e = 0; e < 8; ++e) { const float t = acc[ai][bj][m][e >> 2][e & 3]; ss += t * t; }
;                     ss = sum_fq(ss);
;                     const float rn = rs * __builtin_amdgcn_rsqf(ss * (rs * rs) * (1.0f / 64.0f) + EPS);
;                     float o0[8], o1[8];
; #pragma unroll
;                     for (int e = 0; e < 8; ++e) {
;                         const float cc = cs[e >> 2][e & 3] * rn, sv = sn[e >> 2][e & 3] * rn;
;                         const float q0 = acc[ai][0][m][e >> 2][e & 3] * gv[0][e >> 2][e & 3], q1 = acc[ai][1][m][e >> 2][e & 3] * gv[1][e >> 2][e & 3];
;                         o0[e] = q0 * cc - q1 * sv; o1[e] = q1 * cc + q0 * sv;
;                     }
;                     f16* p = (pn <= 1) ? Q + (size_t)row * 512 + (pn * 4 + wc) * 64 + 8 * fq : K + (size_t)row * 128 + wc * 64 + 8 * fq;
;                     *(u32x4*)p = pack8(o0); *(u32x4*)(p + 32) = pack8(o1);
;                     if (m < 3) {
; #pragma unroll
;                         for (int n = 0; n < 2; ++n) { const f32x4 c2 = cs[n] * c16[n] - sn[n] * s16[n]; sn[n] = sn[n] * c16[n] + cs[n] * s16[n]; cs[n] = c2; }
;                     }
	v_fmac_f32_e32 v148, v56, v56
	v_fmac_f32_e32 v148, v57, v57
	v_fmac_f32_e32 v148, v50, v50
	v_fmac_f32_e32 v148, v51, v51
	v_fmac_f32_e32 v148, v52, v52
	v_fmac_f32_e32 v148, v53, v53
	v_fmac_f32_e32 v148, v22, v22
	v_fmac_f32_e32 v148, v23, v23
	v_fmac_f32_e32 v148, v24, v24
	v_fmac_f32_e32 v148, v25, v25
	v_fmac_f32_e32 v148, v18, v18
	v_fmac_f32_e32 v148, v19, v19
	v_fmac_f32_e32 v148, v20, v20
	v_fmac_f32_e32 v148, v21, v21
	v_mov_b32_e32 v149, v148
	s_nop 1
	v_permlane16_swap_b32_e32 v148, v149
	v_add_f32_e32 v148, v148, v149
	v_mov_b32_e32 v149, v148
	s_nop 1
	v_permlane32_swap_b32_e32 v148, v149
	v_add_f32_e32 v148, v148, v149
	v_mul_f32_e32 v149, v168, v168
	v_mul_f32_e32 v148, v149, v148
	v_fmamk_f32 v148, v148, 0x3c800000, v1
	v_rsq_f32_e32 v165, v148
	v_pk_fma_f32 v[172:173], v[140:141], v[172:173], v[146:147]
	v_pk_mul_f32 v[146:147], v[136:137], v[152:153]
	v_pk_mul_f32 v[148:149], v[134:135], v[208:209]
	v_pk_fma_f32 v[202:203], v[132:133], v[206:207], v[146:147] neg_lo:[0,0,1] neg_hi:[0,0,1]
	v_pk_mul_f32 v[146:147], v[136:137], v[206:207]
	v_mul_f32_e32 v168, v165, v168
	v_pk_fma_f32 v[152:153], v[132:133], v[152:153], v[146:147]
	v_add_u32_e32 v146, 0x90, v164
	v_ashrrev_i32_e32 v147, 31, v146
	v_lshlrev_b64 v[146:147], s0, v[146:147]
	v_pk_mul_f32 v[214:215], v[174:175], v[168:169] op_sel_hi:[1,0]
	v_pk_mul_f32 v[226:227], v[172:173], v[168:169] op_sel_hi:[1,0]
	v_pk_fma_f32 v[150:151], v[130:131], v[150:151], v[148:149]
	v_lshl_add_u64 v[206:207], v[190:191], 0, v[146:147]
	v_pk_mul_f32 v[208:209], v[196:197], v[168:169] op_sel_hi:[1,0]
	v_pk_mul_f32 v[216:217], v[56:57], v[186:187]
	v_pk_mul_f32 v[218:219], v[54:55], v[188:189]
	v_pk_mul_f32 v[146:147], v[212:213], v[214:215]
	v_pk_mul_f32 v[220:221], v[176:177], v[168:169] op_sel_hi:[1,0]
	v_pk_mul_f32 v[148:149], v[210:211], v[226:227]
	v_pk_fma_f32 v[146:147], v[218:219], v[208:209], v[146:147] neg_lo:[0,0,1] neg_hi:[0,0,1]
	v_pk_fma_f32 v[148:149], v[216:217], v[220:221], v[148:149] neg_lo:[0,0,1] neg_hi:[0,0,1]
	v_pk_mul_f32 v[232:233], v[20:21], v[182:183]
	v_pk_mul_f32 v[234:235], v[18:19], v[184:185]
	v_pk_mul_f32 v[236:237], v[150:151], v[168:169] op_sel_hi:[1,0]
	v_pk_mul_f32 v[244:245], v[152:153], v[168:169] op_sel_hi:[1,0]
	v_cvt_pk_f16_f32 v146, v146, v147
	v_cvt_pk_f16_f32 v147, v148, v149
	v_pk_mul_f32 v[230:231], v[204:205], v[168:169] op_sel_hi:[1,0]
	v_pk_mul_f32 v[238:239], v[52:53], v[178:179]
	v_pk_mul_f32 v[240:241], v[50:51], v[180:181]
	v_pk_mul_f32 v[148:149], v[234:235], v[236:237]
	v_pk_mul_f32 v[242:243], v[202:203], v[168:169] op_sel_hi:[1,0]
	v_pk_mul_f32 v[246:247], v[232:233], v[244:245]
	v_pk_fma_f32 v[148:149], v[240:241], v[230:231], v[148:149] neg_lo:[0,0,1] neg_hi:[0,0,1]
	v_pk_fma_f32 v[246:247], v[238:239], v[242:243], v[246:247] neg_lo:[0,0,1] neg_hi:[0,0,1]
	v_cvt_pk_f16_f32 v148, v148, v149
	v_cvt_pk_f16_f32 v149, v246, v247
	global_store_dwordx4 v[206:207], v[146:149], off nt
	s_nop 1
	v_pk_mul_f32 v[146:147], v[212:213], v[208:209]
	v_pk_mul_f32 v[148:149], v[210:211], v[220:221]
	v_pk_fma_f32 v[146:147], v[218:219], v[214:215], v[146:147]
	v_pk_fma_f32 v[148:149], v[216:217], v[226:227], v[148:149]
	v_cvt_pk_f16_f32 v146, v146, v147
	v_cvt_pk_f16_f32 v147, v148, v149
	v_pk_mul_f32 v[148:149], v[234:235], v[230:231]
	v_pk_mul_f32 v[208:209], v[232:233], v[242:243]
	v_pk_fma_f32 v[148:149], v[240:241], v[236:237], v[148:149]
	v_pk_fma_f32 v[208:209], v[238:239], v[244:245], v[208:209]
	v_cvt_pk_f16_f32 v148, v148, v149
	v_cvt_pk_f16_f32 v149, v208, v209
	global_store_dwordx4 v[206:207], v[146:149], off offset:64 nt
	v_pk_mul_f32 v[210:211], v[16:17], v[192:193]
	v_pk_mul_f32 v[212:213], v[14:15], v[200:201]
	v_pk_mul_f32 v[148:149], v[142:143], v[174:175]
	v_pk_mul_f32 v[146:147], v[144:145], v[172:173]
	v_pk_fma_f32 v[208:209], v[138:139], v[196:197], v[148:149] neg_lo:[0,0,1] neg_hi:[0,0,1]
	v_pk_mul_f32 v[148:149], v[142:143], v[196:197]
	v_pk_fma_f32 v[206:207], v[140:141], v[176:177], v[146:147] neg_lo:[0,0,1] neg_hi:[0,0,1]
	v_pk_fma_f32 v[174:175], v[138:139], v[174:175], v[148:149]
	v_pk_mul_f32 v[148:149], v[134:135], v[150:151]
	v_pk_mul_f32 v[146:147], v[144:145], v[176:177]
	v_pk_fma_f32 v[196:197], v[130:131], v[204:205], v[148:149] neg_lo:[0,0,1] neg_hi:[0,0,1]
	v_mul_f32_e32 v148, v47, v47
	v_fmac_f32_e32 v148, v46, v46
	v_fmac_f32_e32 v148, v48, v48
	v_fmac_f32_e32 v148, v49, v49
	v_fmac_f32_e32 v148, v42, v42
	v_fmac_f32_e32 v148, v43, v43
	v_fmac_f32_e32 v148, v44, v44
	v_fmac_f32_e32 v148, v45, v45
	v_fmac_f32_e32 v148, v14, v14
	v_fmac_f32_e32 v148, v15, v15
	v_fmac_f32_e32 v148, v16, v16
	v_fmac_f32_e32 v148, v17, v17
	v_fmac_f32_e32 v148, v10, v10
	v_fmac_f32_e32 v148, v11, v11
	v_fmac_f32_e32 v148, v12, v12
	v_fmac_f32_e32 v148, v13, v13
	v_mov_b32_e32 v149, v148
	s_nop 1
	v_permlane16_swap_b32_e32 v148, v149
	v_add_f32_e32 v148, v148, v149
	v_mov_b32_e32 v149, v148
	s_nop 1
	v_permlane32_swap_b32_e32 v148, v149
	v_add_f32_e32 v148, v148, v149
	v_mul_f32_e32 v149, v166, v166
	v_mul_f32_e32 v148, v149, v148
	v_fmamk_f32 v148, v148, 0x3c800000, v1
	v_rsq_f32_e32 v165, v148
	v_pk_fma_f32 v[172:173], v[140:141], v[172:173], v[146:147]
	v_pk_mul_f32 v[146:147], v[136:137], v[152:153]
	v_pk_mul_f32 v[148:149], v[134:135], v[204:205]
	v_pk_fma_f32 v[176:177], v[132:133], v[202:203], v[146:147] neg_lo:[0,0,1] neg_hi:[0,0,1]
	v_pk_mul_f32 v[146:147], v[136:137], v[202:203]
	v_mul_f32_e32 v166, v165, v166
	v_pk_fma_f32 v[152:153], v[132:133], v[152:153], v[146:147]
	v_add_u32_e32 v146, 0xa0, v164
	v_ashrrev_i32_e32 v147, 31, v146
	v_lshlrev_b64 v[146:147], s0, v[146:147]
	v_pk_mul_f32 v[214:215], v[174:175], v[166:167] op_sel_hi:[1,0]
;     __device__ __forceinline__ void operator()(const f32x4 (&acc)[2][2][4][2], const pg8::Unit& u, int ui, LAS unsigned char* lds, int wr, int wc, int fr_, int fq_) const {
;     ...
;                 for (int m = 0; m < 4; ++m) {
;                     const int row = row0 + ai * 128 + m * 16;
;                     const float rs = rsv[ai * 4 + m];
;                     float ss = 0.f;
; #pragma unroll
;                     for (int bj = 0; bj < 2; ++bj)
; #pragma unroll
;                         for (int e = 0; e < 8; ++e) { const float t = acc[ai][bj][m][e >> 2][e & 3]; ss += t * t; }
;                     ss = sum_fq(ss);
;                     const float rn = rs * __builtin_amdgcn_rsqf(ss * (rs * rs) * (1.0f / 64.0f) + EPS);
;                     float o0[8], o1[8];
; #pragma unroll
;                     for (int e = 0; e < 8; ++e) {
;                         const float cc = cs[e >> 2][e & 3] * rn, sv = sn[e >> 2][e & 3] * rn;
;                         const float q0 = acc[ai][0][m][e >> 2][e & 3] * gv[0][e >> 2][e & 3], q1 = acc[ai][1][m][e >> 2][e & 3] * gv[1][e >> 2][e & 3];
;                         o0[e] = q0 * cc - q1 * sv; o1[e] = q1 * cc + q0 * sv;
;                     }
;                     f16* p = (pn <= 1) ? Q + (size_t)row * 512 + (pn * 4 + wc) * 64 + 8 * fq : K + (size_t)row * 128 + wc * 64 + 8 * fq;
;                     *(u32x4*)p = pack8(o0); *(u32x4*)(p + 32) = pack8(o1);
;                     if (m < 3) {
; #pragma unroll
;                         for (int n = 0; n < 2; ++n) { const f32x4 c2 = cs[n] * c16[n] - sn[n] * s16[n]; sn[n] = sn[n] * c16[n] + cs[n] * s16[n]; cs[n] = c2; }
;                     }
;                 }
	v_pk_mul_f32 v[226:227], v[172:173], v[166:167] op_sel_hi:[1,0]
	v_pk_fma_f32 v[150:151], v[130:131], v[150:151], v[148:149]
	v_lshl_add_u64 v[202:203], v[190:191], 0, v[146:147]
	v_pk_mul_f32 v[204:205], v[208:209], v[166:167] op_sel_hi:[1,0]
	v_pk_mul_f32 v[216:217], v[48:49], v[186:187]
	v_pk_mul_f32 v[218:219], v[46:47], v[188:189]
	v_pk_mul_f32 v[146:147], v[212:213], v[214:215]
	v_pk_mul_f32 v[220:221], v[206:207], v[166:167] op_sel_hi:[1,0]
	v_pk_mul_f32 v[148:149], v[210:211], v[226:227]
	v_pk_fma_f32 v[146:147], v[218:219], v[204:205], v[146:147] neg_lo:[0,0,1] neg_hi:[0,0,1]
	v_pk_fma_f32 v[148:149], v[216:217], v[220:221], v[148:149] neg_lo:[0,0,1] neg_hi:[0,0,1]
	v_pk_mul_f32 v[232:233], v[12:13], v[182:183]
	v_pk_mul_f32 v[234:235], v[10:11], v[184:185]
	v_pk_mul_f32 v[236:237], v[150:151], v[166:167] op_sel_hi:[1,0]
	v_pk_mul_f32 v[244:245], v[152:153], v[166:167] op_sel_hi:[1,0]
	v_cvt_pk_f16_f32 v146, v146, v147
	v_cvt_pk_f16_f32 v147, v148, v149
	v_pk_mul_f32 v[230:231], v[196:197], v[166:167] op_sel_hi:[1,0]
	v_pk_mul_f32 v[238:239], v[44:45], v[178:179]
	v_pk_mul_f32 v[240:241], v[42:43], v[180:181]
	v_pk_mul_f32 v[148:149], v[234:235], v[236:237]
	v_pk_mul_f32 v[242:243], v[176:177], v[166:167] op_sel_hi:[1,0]
	v_pk_mul_f32 v[246:247], v[232:233], v[244:245]
	v_pk_fma_f32 v[148:149], v[240:241], v[230:231], v[148:149] neg_lo:[0,0,1] neg_hi:[0,0,1]
	v_pk_fma_f32 v[246:247], v[238:239], v[242:243], v[246:247] neg_lo:[0,0,1] neg_hi:[0,0,1]
	v_cvt_pk_f16_f32 v148, v148, v149
	v_cvt_pk_f16_f32 v149, v246, v247
	global_store_dwordx4 v[202:203], v[146:149], off nt
	v_pk_mul_f32 v[178:179], v[36:37], v[178:179]
	v_pk_mul_f32 v[180:181], v[34:35], v[180:181]
	v_pk_mul_f32 v[146:147], v[212:213], v[204:205]
	v_pk_mul_f32 v[148:149], v[210:211], v[220:221]
	v_pk_fma_f32 v[146:147], v[218:219], v[214:215], v[146:147]
	v_pk_fma_f32 v[148:149], v[216:217], v[226:227], v[148:149]
	v_cvt_pk_f16_f32 v146, v146, v147
	v_cvt_pk_f16_f32 v147, v148, v149
	v_pk_mul_f32 v[148:149], v[234:235], v[230:231]
	v_pk_mul_f32 v[204:205], v[232:233], v[242:243]
	v_pk_fma_f32 v[148:149], v[240:241], v[236:237], v[148:149]
	v_pk_fma_f32 v[204:205], v[238:239], v[244:245], v[204:205]
	v_cvt_pk_f16_f32 v148, v148, v149
	v_cvt_pk_f16_f32 v149, v204, v205
	global_store_dwordx4 v[202:203], v[146:149], off offset:64 nt
	v_pk_mul_f32 v[202:203], v[136:137], v[152:153]
	v_pk_mul_f32 v[204:205], v[134:135], v[150:151]
	v_pk_mul_f32 v[148:149], v[142:143], v[174:175]
	v_pk_mul_f32 v[142:143], v[142:143], v[208:209]
	v_pk_fma_f32 v[148:149], v[138:139], v[208:209], v[148:149] neg_lo:[0,0,1] neg_hi:[0,0,1]
	v_pk_fma_f32 v[138:139], v[138:139], v[174:175], v[142:143]
	v_mul_f32_e32 v142, v39, v39
	v_fmac_f32_e32 v142, v38, v38
	v_fmac_f32_e32 v142, v40, v40
	v_fmac_f32_e32 v142, v41, v41
	v_fmac_f32_e32 v142, v34, v34
	v_fmac_f32_e32 v142, v35, v35
	v_fmac_f32_e32 v142, v36, v36
	v_fmac_f32_e32 v142, v37, v37
	v_fmac_f32_e32 v142, v6, v6
	v_fmac_f32_e32 v142, v7, v7
	v_fmac_f32_e32 v142, v8, v8
	v_fmac_f32_e32 v142, v9, v9
	v_fmac_f32_e32 v142, v2, v2
	v_fmac_f32_e32 v142, v3, v3
	v_fmac_f32_e32 v142, v4, v4
	v_fmac_f32_e32 v142, v5, v5
	v_mov_b32_e32 v143, v142
	s_nop 1
	v_permlane16_swap_b32_e32 v142, v143
	v_add_f32_e32 v142, v142, v143
	v_mov_b32_e32 v143, v142
	s_nop 1
	v_permlane32_swap_b32_e32 v142, v143
	v_add_f32_e32 v142, v142, v143
	v_mul_f32_e32 v143, v162, v162
	v_mul_f32_e32 v142, v143, v142
	v_fmamk_f32 v142, v142, 0x3c800000, v1
	v_rsq_f32_e32 v142, v142
	v_pk_mul_f32 v[136:137], v[136:137], v[176:177]
	v_pk_mul_f32 v[134:135], v[134:135], v[196:197]
	v_pk_mul_f32 v[146:147], v[144:145], v[172:173]
	v_pk_fma_f32 v[202:203], v[132:133], v[176:177], v[202:203] neg_lo:[0,0,1] neg_hi:[0,0,1]
	v_pk_fma_f32 v[204:205], v[130:131], v[196:197], v[204:205] neg_lo:[0,0,1] neg_hi:[0,0,1]
	v_pk_mul_f32 v[144:145], v[144:145], v[206:207]
	v_pk_fma_f32 v[136:137], v[132:133], v[152:153], v[136:137]
	v_pk_fma_f32 v[132:133], v[130:131], v[150:151], v[134:135]
	v_add_u32_e32 v130, 0xb0, v164
	v_pk_fma_f32 v[146:147], v[140:141], v[206:207], v[146:147] neg_lo:[0,0,1] neg_hi:[0,0,1]
	v_pk_fma_f32 v[140:141], v[140:141], v[172:173], v[144:145]
	v_mul_f32_e32 v134, v142, v162
	v_ashrrev_i32_e32 v131, 31, v130
	v_lshlrev_b64 v[130:131], s0, v[130:131]
	v_pk_mul_f32 v[144:145], v[148:149], v[134:135] op_sel_hi:[1,0]
	v_pk_mul_f32 v[148:149], v[8:9], v[192:193]
	v_pk_mul_f32 v[150:151], v[6:7], v[200:201]
	v_pk_mul_f32 v[138:139], v[138:139], v[134:135] op_sel_hi:[1,0]
	v_pk_mul_f32 v[140:141], v[140:141], v[134:135] op_sel_hi:[1,0]
	v_lshl_add_u64 v[142:143], v[190:191], 0, v[130:131]
	v_pk_mul_f32 v[152:153], v[40:41], v[186:187]
	v_pk_mul_f32 v[164:165], v[38:39], v[188:189]
	v_pk_mul_f32 v[130:131], v[150:151], v[138:139]
	v_pk_mul_f32 v[146:147], v[146:147], v[134:135] op_sel_hi:[1,0]
	v_pk_mul_f32 v[172:173], v[148:149], v[140:141]
	v_pk_fma_f32 v[130:131], v[164:165], v[144:145], v[130:131] neg_lo:[0,0,1] neg_hi:[0,0,1]
	v_pk_fma_f32 v[172:173], v[152:153], v[146:147], v[172:173] neg_lo:[0,0,1] neg_hi:[0,0,1]
	v_cvt_pk_f16_f32 v130, v130, v131
	v_cvt_pk_f16_f32 v131, v172, v173
	v_pk_mul_f32 v[172:173], v[204:205], v[134:135] op_sel_hi:[1,0]
	v_pk_mul_f32 v[174:175], v[4:5], v[182:183]
	v_pk_mul_f32 v[176:177], v[2:3], v[184:185]
	v_pk_mul_f32 v[182:183], v[132:133], v[134:135] op_sel_hi:[1,0]
	v_pk_mul_f32 v[184:185], v[202:203], v[134:135] op_sel_hi:[1,0]
	v_pk_mul_f32 v[134:135], v[136:137], v[134:135] op_sel_hi:[1,0]
	v_pk_mul_f32 v[132:133], v[176:177], v[182:183]
	v_pk_mul_f32 v[136:137], v[174:175], v[134:135]
	v_pk_fma_f32 v[132:133], v[180:181], v[172:173], v[132:133] neg_lo:[0,0,1] neg_hi:[0,0,1]
	v_pk_fma_f32 v[136:137], v[178:179], v[184:185], v[136:137] neg_lo:[0,0,1] neg_hi:[0,0,1]
	v_cvt_pk_f16_f32 v132, v132, v133
	v_cvt_pk_f16_f32 v133, v136, v137
	global_store_dwordx4 v[142:143], v[130:133], off nt
	v_pk_mul_f32 v[136:137], v[174:175], v[184:185]
	s_nop 0
	v_pk_mul_f32 v[130:131], v[150:151], v[144:145]
	v_pk_mul_f32 v[132:133], v[148:149], v[146:147]
	v_pk_fma_f32 v[130:131], v[164:165], v[138:139], v[130:131]
	v_pk_fma_f32 v[132:133], v[152:153], v[140:141], v[132:133]
	v_cvt_pk_f16_f32 v130, v130, v131
	v_cvt_pk_f16_f32 v131, v132, v133
	v_pk_mul_f32 v[132:133], v[176:177], v[172:173]
	v_pk_fma_f32 v[134:135], v[178:179], v[134:135], v[136:137]
	v_pk_fma_f32 v[132:133], v[180:181], v[182:183], v[132:133]
	s_nop 0
	v_cvt_pk_f16_f32 v132, v132, v133
	v_cvt_pk_f16_f32 v133, v134, v135
	global_store_dwordx4 v[142:143], v[130:133], off offset:64 nt
	s_add_u32 s0, s52, 0xffffff00
	s_addc_u32 s1, s53, -1
	s_andn2_b64 vcc, exec, s[6:7]
	s_cbranch_vccz .LBB0_215
